# s_setprio A/B: mid-segment s_setprio 0/1 flip pairs removed from all five GEMM K-loops (priority stays raised across each 32-MFMA segment)
# speedup vs baseline: 1.0160x; 1.0160x over previous
; #define PG8_STAGE(bufoff, gbase, voff) do { _Pragma("unroll") for (int _i = 0; _i < 2; ++_i) \
;         __builtin_amdgcn_global_load_lds((const unsigned*)((const char*)(gbase) + (voff)[_i]), (LAS unsigned*)(lds + (bufoff) + ldsw + _i * 8192), 16, 0, 0); } while (0)
; #define PG8_LDA(dst, b, h) do { _Pragma("unroll") for (int m = 0; m < 4; ++m) _Pragma("unroll") for (int k = 0; k < 2; ++k) dst[m][k] = *(const LAS bf16x8*)(lds + PG8_SA(b, h) + aoff + m * 2048 + k * 1024); } while (0)
; #define PG8_LDB(dst, b, h) do { _Pragma("unroll") for (int n = 0; n < 2; ++n) _Pragma("unroll") for (int k = 0; k < 2; ++k) dst[n][k] = *(const LAS bf16x8*)(lds + PG8_SB(b, h) + boff + n * 2048 + k * 1024); } while (0)
; #define PG8_MMA(ai, bj, At, Bt) do { __builtin_amdgcn_s_setprio(1); _Pragma("unroll") for (int m = 0; m < 4; ++m) _Pragma("unroll") for (int n = 0; n < 2; ++n) _Pragma("unroll") for (int k = 0; k < 2; ++k) \
;         acc[ai][bj][m][n] = MFMA16(Bt[n][k], At[m][k], acc[ai][bj][m][n]); __builtin_amdgcn_s_setprio(0); } while (0)
; #define PG8_WAIT_V(n) asm volatile("s_waitcnt vmcnt(" #n ")" ::: "memory")
; #define PG8_WAIT_L(n) asm volatile("s_waitcnt lgkmcnt(" #n ")" ::: "memory")
; #define PG8_BAR __builtin_amdgcn_s_barrier()
; #define PG8_SCHED __builtin_amdgcn_sched_barrier(0)
; template <class Epi>
; __device__ __forceinline__ void gemm_phase(LAS unsigned char* lds, const Gemm g, const StaticOrder& S, const Epi& E, int tid_) {
;     ...
;             const bool last = (t == nt - 2);
;             const char* a1 = cA + (size_t)(t + 1) * kstep;
;             const char* a2 = last ? nA : cA + (size_t)(t + 2) * kstep; const char* b2 = last ? nB : cB + (size_t)(t + 2) * kstep;
;             const char* a3 = a2 + kstep; const char* b3 = b2 + kstep;
;             PG8_LDB(B0, 0, 0); PG8_LDB(B1, 0, 1); PG8_SCHED; PG8_LDA(At, 0, 0); PG8_STAGE(PG8_SA(1, 1), a1 + hsA, voffA);
;             PG8_WAIT_V(8); PG8_WAIT_L(0); PG8_BAR; PG8_MMA(0, 0, At, B0); PG8_MMA(0, 1, At, B1); PG8_BAR; PG8_SCHED;
;             PG8_LDA(At, 0, 1); PG8_STAGE(PG8_SB(0, 0), b2, voffB); PG8_STAGE(PG8_SB(0, 1), b2 + hsB, voffB); PG8_STAGE(PG8_SA(0, 0), a2, voffA);
;             PG8_WAIT_V(8); PG8_WAIT_L(0); PG8_BAR; PG8_MMA(1, 0, At, B0); PG8_MMA(1, 1, At, B1); PG8_BAR; PG8_SCHED;
.LBB0_85:
	s_add_i32 s70, s40, 2
	s_add_u32 s41, s28, 0xfffc0080
	s_addc_u32 s56, s29, -1
	s_add_i32 s71, 0, 0x10000
	s_cmp_eq_u32 s64, s40
	s_cselect_b32 s57, s22, s56
	s_cselect_b32 s56, s23, s41
	s_cselect_b32 s41, s27, s69
	s_cselect_b32 s40, s51, s68
	s_add_i32 s74, 0, 0x14000
	v_add_u32_e32 v142, s71, v165
	v_add_u32_e32 v162, s74, v165
	ds_read_b128 v[130:133], v142
	ds_read_b128 v[134:137], v142 offset:1024
	ds_read_b128 v[138:141], v142 offset:2048
	ds_read_b128 v[142:145], v142 offset:3072
	ds_read_b128 v[158:161], v162
	ds_read_b128 v[174:177], v162 offset:1024
	ds_read_b128 v[178:181], v162 offset:2048
	ds_read_b128 v[198:201], v162 offset:3072
	v_lshl_add_u64 v[162:163], s[28:29], 0, v[154:155]
	s_add_i32 m0, s58, 0xc000
	ds_read_b128 v[202:205], v172
	ds_read_b128 v[206:209], v172 offset:1024
	ds_read_b128 v[216:219], v172 offset:2048
	ds_read_b128 v[220:223], v172 offset:3072
	ds_read_b128 v[224:227], v172 offset:4096
	ds_read_b128 v[228:231], v172 offset:5120
	ds_read_b128 v[232:235], v172 offset:6144
	ds_read_b128 v[236:239], v172 offset:7168
	global_load_lds_dwordx4 v[162:163], off
	v_lshl_add_u64 v[162:163], s[28:29], 0, v[156:157]
	s_add_i32 m0, s58, 0xe000
	s_nop 0
	global_load_lds_dwordx4 v[162:163], off
	s_waitcnt vmcnt(8)
	s_waitcnt lgkmcnt(0)
	s_barrier
	s_setprio 1
	s_waitcnt lgkmcnt(0)
	v_mfma_f32_16x16x32_bf16 v[122:125], v[130:133], v[202:205], v[122:125]
	v_mfma_f32_16x16x32_bf16 v[118:121], v[138:141], v[202:205], v[118:121]
	v_mfma_f32_16x16x32_bf16 v[110:113], v[130:133], v[216:219], v[110:113]
	v_mfma_f32_16x16x32_bf16 v[102:105], v[138:141], v[216:219], v[102:105]
	v_mfma_f32_16x16x32_bf16 v[94:97], v[130:133], v[224:227], v[94:97]
	v_mfma_f32_16x16x32_bf16 v[86:89], v[138:141], v[224:227], v[86:89]
	v_mfma_f32_16x16x32_bf16 v[76:79], v[130:133], v[232:235], v[76:79]
	v_mfma_f32_16x16x32_bf16 v[68:71], v[138:141], v[232:235], v[68:71]
	v_mfma_f32_16x16x32_bf16 v[122:125], v[134:137], v[206:209], v[122:125]
	v_mfma_f32_16x16x32_bf16 v[118:121], v[142:145], v[206:209], v[118:121]
	v_mfma_f32_16x16x32_bf16 v[110:113], v[134:137], v[220:223], v[110:113]
	v_mfma_f32_16x16x32_bf16 v[102:105], v[142:145], v[220:223], v[102:105]
	v_mfma_f32_16x16x32_bf16 v[94:97], v[134:137], v[228:231], v[94:97]
	v_mfma_f32_16x16x32_bf16 v[86:89], v[142:145], v[228:231], v[86:89]
	v_mfma_f32_16x16x32_bf16 v[76:79], v[134:137], v[236:239], v[76:79]
	v_mfma_f32_16x16x32_bf16 v[68:71], v[142:145], v[236:239], v[68:71]
	v_mfma_f32_16x16x32_bf16 v[126:129], v[158:161], v[202:205], v[126:129]
	v_mfma_f32_16x16x32_bf16 v[114:117], v[178:181], v[202:205], v[114:117]
	v_mfma_f32_16x16x32_bf16 v[106:109], v[158:161], v[216:219], v[106:109]
	v_mfma_f32_16x16x32_bf16 v[98:101], v[178:181], v[216:219], v[98:101]
	v_mfma_f32_16x16x32_bf16 v[90:93], v[158:161], v[224:227], v[90:93]
	v_mfma_f32_16x16x32_bf16 v[82:85], v[178:181], v[224:227], v[82:85]
	v_mfma_f32_16x16x32_bf16 v[72:75], v[158:161], v[232:235], v[72:75]
	v_mfma_f32_16x16x32_bf16 v[64:67], v[178:181], v[232:235], v[64:67]
	v_mfma_f32_16x16x32_bf16 v[126:129], v[174:177], v[206:209], v[126:129]
	v_mfma_f32_16x16x32_bf16 v[114:117], v[198:201], v[206:209], v[114:117]
	v_mfma_f32_16x16x32_bf16 v[106:109], v[174:177], v[220:223], v[106:109]
	v_mfma_f32_16x16x32_bf16 v[98:101], v[198:201], v[220:223], v[98:101]
	v_mfma_f32_16x16x32_bf16 v[90:93], v[174:177], v[228:231], v[90:93]
	v_mfma_f32_16x16x32_bf16 v[82:85], v[198:201], v[228:231], v[82:85]
	v_mfma_f32_16x16x32_bf16 v[72:75], v[174:177], v[236:239], v[72:75]
	v_mfma_f32_16x16x32_bf16 v[64:67], v[198:201], v[236:239], v[64:67]
	s_setprio 0
	s_barrier
	s_add_i32 s71, s71, s31
	v_lshl_add_u64 v[162:163], s[40:41], 0, v[150:151]
	s_mov_b32 m0, s71
	ds_read_b128 v[202:205], v172 offset:16384
	ds_read_b128 v[206:209], v172 offset:17408
	ds_read_b128 v[216:219], v172 offset:18432
	ds_read_b128 v[220:223], v172 offset:19456
	ds_read_b128 v[224:227], v172 offset:20480
	ds_read_b128 v[228:231], v172 offset:21504
	ds_read_b128 v[232:235], v172 offset:22528
	ds_read_b128 v[236:239], v172 offset:23552
	global_load_lds_dwordx4 v[162:163], off
	s_add_i32 m0, s71, 0x2000
	s_add_u32 s72, s40, 0x40000
	v_lshl_add_u64 v[240:241], s[40:41], 0, v[146:147]
	s_addc_u32 s73, s41, 0
	s_add_i32 s71, s74, s31
	global_load_lds_dwordx4 v[240:241], off
	v_lshl_add_u64 v[242:243], s[72:73], 0, v[150:151]
	s_mov_b32 m0, s71
	v_lshl_add_u64 v[244:245], s[56:57], 0, v[148:149]
	global_load_lds_dwordx4 v[242:243], off
	v_lshl_add_u64 v[242:243], s[72:73], 0, v[146:147]
	s_add_i32 m0, s71, 0x2000
	s_nop 0
	global_load_lds_dwordx4 v[242:243], off
	v_lshl_add_u64 v[242:243], s[56:57], 0, v[152:153]
	s_mov_b32 m0, s58
	s_nop 0
	global_load_lds_dwordx4 v[242:243], off
	s_mov_b32 m0, s59
	s_nop 0
	global_load_lds_dwordx4 v[244:245], off
	s_waitcnt vmcnt(8)
	s_waitcnt lgkmcnt(0)
	s_barrier
; #define PG8_STAGE(bufoff, gbase, voff) do { _Pragma("unroll") for (int _i = 0; _i < 2; ++_i) \
;         __builtin_amdgcn_global_load_lds((const unsigned*)((const char*)(gbase) + (voff)[_i]), (LAS unsigned*)(lds + (bufoff) + ldsw + _i * 8192), 16, 0, 0); } while (0)
; #define PG8_LDA(dst, b, h) do { _Pragma("unroll") for (int m = 0; m < 4; ++m) _Pragma("unroll") for (int k = 0; k < 2; ++k) dst[m][k] = *(const LAS bf16x8*)(lds + PG8_SA(b, h) + aoff + m * 2048 + k * 1024); } while (0)
; #define PG8_LDB(dst, b, h) do { _Pragma("unroll") for (int n = 0; n < 2; ++n) _Pragma("unroll") for (int k = 0; k < 2; ++k) dst[n][k] = *(const LAS bf16x8*)(lds + PG8_SB(b, h) + boff + n * 2048 + k * 1024); } while (0)
; #define PG8_MMA(ai, bj, At, Bt) do { __builtin_amdgcn_s_setprio(1); _Pragma("unroll") for (int m = 0; m < 4; ++m) _Pragma("unroll") for (int n = 0; n < 2; ++n) _Pragma("unroll") for (int k = 0; k < 2; ++k) \
;         acc[ai][bj][m][n] = MFMA16(Bt[n][k], At[m][k], acc[ai][bj][m][n]); __builtin_amdgcn_s_setprio(0); } while (0)
; #define PG8_WAIT_V(n) asm volatile("s_waitcnt vmcnt(" #n ")" ::: "memory")
; #define PG8_WAIT_L(n) asm volatile("s_waitcnt lgkmcnt(" #n ")" ::: "memory")
; #define PG8_BAR __builtin_amdgcn_s_barrier()
; #define PG8_SCHED __builtin_amdgcn_sched_barrier(0)
; template <class Epi>
; __device__ __forceinline__ void gemm_phase(LAS unsigned char* lds, const Gemm g, const StaticOrder& S, const Epi& E, int tid_) {
;     ...
;             PG8_WAIT_V(8); PG8_WAIT_L(0); PG8_BAR; PG8_MMA(1, 0, At, B0); PG8_MMA(1, 1, At, B1); PG8_BAR; PG8_SCHED;
;             PG8_LDB(B0, 1, 0); PG8_LDB(B1, 1, 1); PG8_SCHED; PG8_LDA(At, 1, 0); PG8_STAGE(PG8_SA(0, 1), a2 + hsA, voffA);
;             PG8_WAIT_V(8); PG8_WAIT_L(0); PG8_BAR; PG8_MMA(0, 0, At, B0); PG8_MMA(0, 1, At, B1); PG8_BAR; PG8_SCHED;
	s_setprio 1
	s_waitcnt lgkmcnt(0)
	v_mfma_f32_16x16x32_bf16 v[60:63], v[130:133], v[202:205], v[60:63]
	v_mfma_f32_16x16x32_bf16 v[52:55], v[138:141], v[202:205], v[52:55]
	v_mfma_f32_16x16x32_bf16 v[44:47], v[130:133], v[216:219], v[44:47]
	v_mfma_f32_16x16x32_bf16 v[36:39], v[138:141], v[216:219], v[36:39]
	v_mfma_f32_16x16x32_bf16 v[28:31], v[130:133], v[224:227], v[28:31]
	v_mfma_f32_16x16x32_bf16 v[20:23], v[138:141], v[224:227], v[20:23]
	v_mfma_f32_16x16x32_bf16 v[12:15], v[130:133], v[232:235], v[12:15]
	v_mfma_f32_16x16x32_bf16 v[4:7], v[138:141], v[232:235], v[4:7]
	v_mfma_f32_16x16x32_bf16 v[60:63], v[134:137], v[206:209], v[60:63]
	v_mfma_f32_16x16x32_bf16 v[52:55], v[142:145], v[206:209], v[52:55]
	v_mfma_f32_16x16x32_bf16 v[44:47], v[134:137], v[220:223], v[44:47]
	v_mfma_f32_16x16x32_bf16 v[36:39], v[142:145], v[220:223], v[36:39]
	v_mfma_f32_16x16x32_bf16 v[28:31], v[134:137], v[228:231], v[28:31]
	v_mfma_f32_16x16x32_bf16 v[20:23], v[142:145], v[228:231], v[20:23]
	v_mfma_f32_16x16x32_bf16 v[12:15], v[134:137], v[236:239], v[12:15]
	v_mfma_f32_16x16x32_bf16 v[4:7], v[142:145], v[236:239], v[4:7]
	v_mfma_f32_16x16x32_bf16 v[56:59], v[158:161], v[202:205], v[56:59]
	v_mfma_f32_16x16x32_bf16 v[48:51], v[178:181], v[202:205], v[48:51]
	v_mfma_f32_16x16x32_bf16 v[40:43], v[158:161], v[216:219], v[40:43]
	v_mfma_f32_16x16x32_bf16 v[32:35], v[178:181], v[216:219], v[32:35]
	v_mfma_f32_16x16x32_bf16 v[24:27], v[158:161], v[224:227], v[24:27]
	v_mfma_f32_16x16x32_bf16 v[16:19], v[178:181], v[224:227], v[16:19]
	v_mfma_f32_16x16x32_bf16 v[8:11], v[158:161], v[232:235], v[8:11]
	v_mfma_f32_16x16x32_bf16 v[0:3], v[178:181], v[232:235], v[0:3]
	v_mfma_f32_16x16x32_bf16 v[56:59], v[174:177], v[206:209], v[56:59]
	v_mfma_f32_16x16x32_bf16 v[48:51], v[198:201], v[206:209], v[48:51]
	v_mfma_f32_16x16x32_bf16 v[40:43], v[174:177], v[220:223], v[40:43]
	v_mfma_f32_16x16x32_bf16 v[32:35], v[198:201], v[220:223], v[32:35]
	v_mfma_f32_16x16x32_bf16 v[24:27], v[174:177], v[228:231], v[24:27]
	v_mfma_f32_16x16x32_bf16 v[16:19], v[198:201], v[228:231], v[16:19]
	v_mfma_f32_16x16x32_bf16 v[8:11], v[174:177], v[236:239], v[8:11]
	v_mfma_f32_16x16x32_bf16 v[0:3], v[198:201], v[236:239], v[0:3]
	s_setprio 0
	s_barrier
	s_add_i32 s71, 0, 0x18000
	s_add_i32 s72, 0, 0x1c000
	v_add_u32_e32 v142, s71, v165
	v_add_u32_e32 v173, s72, v165
	ds_read_b128 v[130:133], v142
	ds_read_b128 v[134:137], v142 offset:1024
	ds_read_b128 v[138:141], v142 offset:2048
	ds_read_b128 v[142:145], v142 offset:3072
	ds_read_b128 v[158:161], v173
	ds_read_b128 v[174:177], v173 offset:1024
	ds_read_b128 v[178:181], v173 offset:2048
	ds_read_b128 v[198:201], v173 offset:3072
	s_add_u32 s56, s56, 0x40000
	s_addc_u32 s57, s57, 0
	s_mov_b32 m0, s60
	v_lshl_add_u64 v[246:247], s[56:57], 0, v[152:153]
	ds_read_b128 v[202:205], v172 offset:32768
	ds_read_b128 v[206:209], v172 offset:33792
	ds_read_b128 v[216:219], v172 offset:34816
	ds_read_b128 v[220:223], v172 offset:35840
	ds_read_b128 v[224:227], v172 offset:36864
	ds_read_b128 v[228:231], v172 offset:37888
	ds_read_b128 v[232:235], v172 offset:38912
	ds_read_b128 v[236:239], v172 offset:39936
	global_load_lds_dwordx4 v[246:247], off
	v_lshl_add_u64 v[246:247], s[56:57], 0, v[148:149]
	s_mov_b32 m0, s61
	s_nop 0
	global_load_lds_dwordx4 v[246:247], off
	s_waitcnt vmcnt(8)
	s_waitcnt lgkmcnt(0)
	s_barrier
	s_setprio 1
	s_waitcnt lgkmcnt(0)
	v_mfma_f32_16x16x32_bf16 v[122:125], v[130:133], v[202:205], v[122:125]
	v_mfma_f32_16x16x32_bf16 v[118:121], v[138:141], v[202:205], v[118:121]
	v_mfma_f32_16x16x32_bf16 v[110:113], v[130:133], v[216:219], v[110:113]
	v_mfma_f32_16x16x32_bf16 v[102:105], v[138:141], v[216:219], v[102:105]
	v_mfma_f32_16x16x32_bf16 v[94:97], v[130:133], v[224:227], v[94:97]
	v_mfma_f32_16x16x32_bf16 v[86:89], v[138:141], v[224:227], v[86:89]
	v_mfma_f32_16x16x32_bf16 v[76:79], v[130:133], v[232:235], v[76:79]
	v_mfma_f32_16x16x32_bf16 v[68:71], v[138:141], v[232:235], v[68:71]
	v_mfma_f32_16x16x32_bf16 v[122:125], v[134:137], v[206:209], v[122:125]
	v_mfma_f32_16x16x32_bf16 v[118:121], v[142:145], v[206:209], v[118:121]
	v_mfma_f32_16x16x32_bf16 v[110:113], v[134:137], v[220:223], v[110:113]
	v_mfma_f32_16x16x32_bf16 v[102:105], v[142:145], v[220:223], v[102:105]
	v_mfma_f32_16x16x32_bf16 v[94:97], v[134:137], v[228:231], v[94:97]
	v_mfma_f32_16x16x32_bf16 v[86:89], v[142:145], v[228:231], v[86:89]
	v_mfma_f32_16x16x32_bf16 v[76:79], v[134:137], v[236:239], v[76:79]
	v_mfma_f32_16x16x32_bf16 v[68:71], v[142:145], v[236:239], v[68:71]
	v_mfma_f32_16x16x32_bf16 v[126:129], v[158:161], v[202:205], v[126:129]
	v_mfma_f32_16x16x32_bf16 v[114:117], v[178:181], v[202:205], v[114:117]
	v_mfma_f32_16x16x32_bf16 v[106:109], v[158:161], v[216:219], v[106:109]
	v_mfma_f32_16x16x32_bf16 v[98:101], v[178:181], v[216:219], v[98:101]
	v_mfma_f32_16x16x32_bf16 v[90:93], v[158:161], v[224:227], v[90:93]
	v_mfma_f32_16x16x32_bf16 v[82:85], v[178:181], v[224:227], v[82:85]
	v_mfma_f32_16x16x32_bf16 v[72:75], v[158:161], v[232:235], v[72:75]
	v_mfma_f32_16x16x32_bf16 v[64:67], v[178:181], v[232:235], v[64:67]
	v_mfma_f32_16x16x32_bf16 v[126:129], v[174:177], v[206:209], v[126:129]
	v_mfma_f32_16x16x32_bf16 v[114:117], v[198:201], v[206:209], v[114:117]
	v_mfma_f32_16x16x32_bf16 v[106:109], v[174:177], v[220:223], v[106:109]
	v_mfma_f32_16x16x32_bf16 v[98:101], v[198:201], v[220:223], v[98:101]
	v_mfma_f32_16x16x32_bf16 v[90:93], v[174:177], v[228:231], v[90:93]
	v_mfma_f32_16x16x32_bf16 v[82:85], v[198:201], v[228:231], v[82:85]
	v_mfma_f32_16x16x32_bf16 v[72:75], v[174:177], v[236:239], v[72:75]
	v_mfma_f32_16x16x32_bf16 v[64:67], v[198:201], v[236:239], v[64:67]
	s_setprio 0
	s_barrier
; #define PG8_STAGE(bufoff, gbase, voff) do { _Pragma("unroll") for (int _i = 0; _i < 2; ++_i) \
;         __builtin_amdgcn_global_load_lds((const unsigned*)((const char*)(gbase) + (voff)[_i]), (LAS unsigned*)(lds + (bufoff) + ldsw + _i * 8192), 16, 0, 0); } while (0)
; #define PG8_LDA(dst, b, h) do { _Pragma("unroll") for (int m = 0; m < 4; ++m) _Pragma("unroll") for (int k = 0; k < 2; ++k) dst[m][k] = *(const LAS bf16x8*)(lds + PG8_SA(b, h) + aoff + m * 2048 + k * 1024); } while (0)
; #define PG8_MMA(ai, bj, At, Bt) do { __builtin_amdgcn_s_setprio(1); _Pragma("unroll") for (int m = 0; m < 4; ++m) _Pragma("unroll") for (int n = 0; n < 2; ++n) _Pragma("unroll") for (int k = 0; k < 2; ++k) \
;         acc[ai][bj][m][n] = MFMA16(Bt[n][k], At[m][k], acc[ai][bj][m][n]); __builtin_amdgcn_s_setprio(0); } while (0)
; #define PG8_WAIT_V(n) asm volatile("s_waitcnt vmcnt(" #n ")" ::: "memory")
; #define PG8_WAIT_L(n) asm volatile("s_waitcnt lgkmcnt(" #n ")" ::: "memory")
; #define PG8_BAR __builtin_amdgcn_s_barrier()
; #define PG8_SCHED __builtin_amdgcn_sched_barrier(0)
; template <class Epi>
; __device__ __forceinline__ void gemm_phase(LAS unsigned char* lds, const Gemm g, const StaticOrder& S, const Epi& E, int tid_) {
;     ...
;         for (int t = 0; t < nt; t += 2) {
;     ...
;             PG8_LDA(At, 1, 1); PG8_STAGE(PG8_SB(1, 0), b3, voffB); PG8_STAGE(PG8_SB(1, 1), b3 + hsB, voffB); PG8_STAGE(PG8_SA(1, 0), a3, voffA);
;             PG8_WAIT_V(8); PG8_WAIT_L(0); PG8_BAR; PG8_MMA(1, 0, At, B0); PG8_MMA(1, 1, At, B1); PG8_BAR; PG8_SCHED;
;         }
	s_add_i32 s56, s71, s31
	v_lshl_add_u64 v[162:163], v[162:163], 0, s[6:7]
	s_mov_b32 m0, s56
	ds_read_b128 v[202:205], v172 offset:49152
	ds_read_b128 v[206:209], v172 offset:50176
	ds_read_b128 v[216:219], v172 offset:51200
	ds_read_b128 v[220:223], v172 offset:52224
	ds_read_b128 v[224:227], v172 offset:53248
	ds_read_b128 v[228:231], v172 offset:54272
	ds_read_b128 v[232:235], v172 offset:55296
	ds_read_b128 v[236:239], v172 offset:56320
	global_load_lds_dwordx4 v[162:163], off
	s_add_i32 m0, s56, 0x2000
	s_add_u32 s40, s40, 0x40080
	v_lshl_add_u64 v[162:163], v[240:241], 0, s[6:7]
	s_addc_u32 s41, s41, 0
	s_add_i32 s56, s72, s31
	global_load_lds_dwordx4 v[162:163], off
	v_lshl_add_u64 v[162:163], s[40:41], 0, v[150:151]
	s_mov_b32 m0, s56
	s_nop 0
	global_load_lds_dwordx4 v[162:163], off
	v_lshl_add_u64 v[162:163], s[40:41], 0, v[146:147]
	s_add_i32 m0, s56, 0x2000
	s_nop 0
	global_load_lds_dwordx4 v[162:163], off
	v_lshl_add_u64 v[162:163], v[242:243], 0, s[6:7]
	s_mov_b32 m0, s62
	s_nop 0
	global_load_lds_dwordx4 v[162:163], off
	v_lshl_add_u64 v[162:163], v[244:245], 0, s[6:7]
	s_mov_b32 m0, s63
	s_nop 0
	global_load_lds_dwordx4 v[162:163], off
	s_waitcnt vmcnt(8)
	s_waitcnt lgkmcnt(0)
	s_barrier
	s_setprio 1
	s_waitcnt lgkmcnt(0)
	v_mfma_f32_16x16x32_bf16 v[60:63], v[130:133], v[202:205], v[60:63]
	v_mfma_f32_16x16x32_bf16 v[52:55], v[138:141], v[202:205], v[52:55]
	v_mfma_f32_16x16x32_bf16 v[44:47], v[130:133], v[216:219], v[44:47]
	v_mfma_f32_16x16x32_bf16 v[36:39], v[138:141], v[216:219], v[36:39]
	v_mfma_f32_16x16x32_bf16 v[28:31], v[130:133], v[224:227], v[28:31]
	v_mfma_f32_16x16x32_bf16 v[20:23], v[138:141], v[224:227], v[20:23]
	v_mfma_f32_16x16x32_bf16 v[12:15], v[130:133], v[232:235], v[12:15]
	v_mfma_f32_16x16x32_bf16 v[4:7], v[138:141], v[232:235], v[4:7]
	v_mfma_f32_16x16x32_bf16 v[60:63], v[134:137], v[206:209], v[60:63]
	v_mfma_f32_16x16x32_bf16 v[52:55], v[142:145], v[206:209], v[52:55]
	v_mfma_f32_16x16x32_bf16 v[44:47], v[134:137], v[220:223], v[44:47]
	v_mfma_f32_16x16x32_bf16 v[36:39], v[142:145], v[220:223], v[36:39]
	v_mfma_f32_16x16x32_bf16 v[28:31], v[134:137], v[228:231], v[28:31]
	v_mfma_f32_16x16x32_bf16 v[20:23], v[142:145], v[228:231], v[20:23]
	v_mfma_f32_16x16x32_bf16 v[12:15], v[134:137], v[236:239], v[12:15]
	v_mfma_f32_16x16x32_bf16 v[4:7], v[142:145], v[236:239], v[4:7]
	v_mfma_f32_16x16x32_bf16 v[56:59], v[158:161], v[202:205], v[56:59]
	v_mfma_f32_16x16x32_bf16 v[48:51], v[178:181], v[202:205], v[48:51]
	v_mfma_f32_16x16x32_bf16 v[40:43], v[158:161], v[216:219], v[40:43]
	v_mfma_f32_16x16x32_bf16 v[32:35], v[178:181], v[216:219], v[32:35]
	v_mfma_f32_16x16x32_bf16 v[24:27], v[158:161], v[224:227], v[24:27]
	v_mfma_f32_16x16x32_bf16 v[16:19], v[178:181], v[224:227], v[16:19]
	v_mfma_f32_16x16x32_bf16 v[8:11], v[158:161], v[232:235], v[8:11]
	v_mfma_f32_16x16x32_bf16 v[0:3], v[178:181], v[232:235], v[0:3]
	v_mfma_f32_16x16x32_bf16 v[56:59], v[174:177], v[206:209], v[56:59]
	v_mfma_f32_16x16x32_bf16 v[48:51], v[198:201], v[206:209], v[48:51]
	v_mfma_f32_16x16x32_bf16 v[40:43], v[174:177], v[220:223], v[40:43]
	v_mfma_f32_16x16x32_bf16 v[32:35], v[198:201], v[220:223], v[32:35]
	v_mfma_f32_16x16x32_bf16 v[24:27], v[174:177], v[228:231], v[24:27]
	v_mfma_f32_16x16x32_bf16 v[16:19], v[198:201], v[228:231], v[16:19]
	v_mfma_f32_16x16x32_bf16 v[8:11], v[174:177], v[236:239], v[8:11]
	v_mfma_f32_16x16x32_bf16 v[0:3], v[198:201], v[236:239], v[0:3]
	s_setprio 0
	s_barrier
	s_add_u32 s28, s28, 0x100
	s_addc_u32 s29, s29, 0
	s_add_u32 s68, s68, 0x100
	s_addc_u32 s69, s69, 0
	s_cmp_ge_i32 s70, s30
	s_mov_b32 s40, s70
	s_cbranch_scc0 .LBB0_85
	s_and_b64 vcc, exec, s[48:49]
	s_cbranch_vccz .LBB0_88

; #define PG8_STAGE(bufoff, gbase, voff) do { _Pragma("unroll") for (int _i = 0; _i < 2; ++_i) \
;         __builtin_amdgcn_global_load_lds((const unsigned*)((const char*)(gbase) + (voff)[_i]), (LAS unsigned*)(lds + (bufoff) + ldsw + _i * 8192), 16, 0, 0); } while (0)
; #define PG8_LDA(dst, b, h) do { _Pragma("unroll") for (int m = 0; m < 4; ++m) _Pragma("unroll") for (int k = 0; k < 2; ++k) dst[m][k] = *(const LAS bf16x8*)(lds + PG8_SA(b, h) + aoff + m * 2048 + k * 1024); } while (0)
; #define PG8_LDB(dst, b, h) do { _Pragma("unroll") for (int n = 0; n < 2; ++n) _Pragma("unroll") for (int k = 0; k < 2; ++k) dst[n][k] = *(const LAS bf16x8*)(lds + PG8_SB(b, h) + boff + n * 2048 + k * 1024); } while (0)
; #define PG8_MMA(ai, bj, At, Bt) do { __builtin_amdgcn_s_setprio(1); _Pragma("unroll") for (int m = 0; m < 4; ++m) _Pragma("unroll") for (int n = 0; n < 2; ++n) _Pragma("unroll") for (int k = 0; k < 2; ++k) \
;         acc[ai][bj][m][n] = MFMA16(Bt[n][k], At[m][k], acc[ai][bj][m][n]); __builtin_amdgcn_s_setprio(0); } while (0)
; #define PG8_WAIT_V(n) asm volatile("s_waitcnt vmcnt(" #n ")" ::: "memory")
; #define PG8_WAIT_L(n) asm volatile("s_waitcnt lgkmcnt(" #n ")" ::: "memory")
; #define PG8_BAR __builtin_amdgcn_s_barrier()
; #define PG8_SCHED __builtin_amdgcn_sched_barrier(0)
; template <class Epi>
; __device__ __forceinline__ void gemm_phase(LAS unsigned char* lds, const Gemm g, const StaticOrder& S, const Epi& E, int tid_) {
;     ...
;             const bool last = (t == nt - 2);
;             const char* a1 = cA + (size_t)(t + 1) * kstep;
;             const char* a2 = last ? nA : cA + (size_t)(t + 2) * kstep; const char* b2 = last ? nB : cB + (size_t)(t + 2) * kstep;
;             const char* a3 = a2 + kstep; const char* b3 = b2 + kstep;
;             PG8_LDB(B0, 0, 0); PG8_LDB(B1, 0, 1); PG8_SCHED; PG8_LDA(At, 0, 0); PG8_STAGE(PG8_SA(1, 1), a1 + hsA, voffA);
;             PG8_WAIT_V(8); PG8_WAIT_L(0); PG8_BAR; PG8_MMA(0, 0, At, B0); PG8_MMA(0, 1, At, B1); PG8_BAR; PG8_SCHED;
;             PG8_LDA(At, 0, 1); PG8_STAGE(PG8_SB(0, 0), b2, voffB); PG8_STAGE(PG8_SB(0, 1), b2 + hsB, voffB); PG8_STAGE(PG8_SA(0, 0), a2, voffA);
;             PG8_WAIT_V(8); PG8_WAIT_L(0); PG8_BAR; PG8_MMA(1, 0, At, B0); PG8_MMA(1, 1, At, B1); PG8_BAR; PG8_SCHED;
.LBB0_172:
	s_add_i32 s74, s40, 2
	s_add_u32 s41, s28, 0xfffc0080
	s_addc_u32 s60, s29, -1
	s_add_i32 s75, 0, 0x10000
	s_cmp_eq_u32 s68, s40
	s_cselect_b32 s61, s22, s60
	s_cselect_b32 s60, s23, s41
	s_cselect_b32 s41, s49, s73
	s_cselect_b32 s40, s55, s72
	s_add_i32 s78, 0, 0x14000
	v_add_u32_e32 v142, s75, v165
	v_add_u32_e32 v162, s78, v165
	ds_read_b128 v[130:133], v142
	ds_read_b128 v[134:137], v142 offset:1024
	ds_read_b128 v[138:141], v142 offset:2048
	ds_read_b128 v[142:145], v142 offset:3072
	ds_read_b128 v[158:161], v162
	ds_read_b128 v[174:177], v162 offset:1024
	ds_read_b128 v[178:181], v162 offset:2048
	ds_read_b128 v[198:201], v162 offset:3072
	v_lshl_add_u64 v[162:163], s[28:29], 0, v[154:155]
	s_add_i32 m0, s43, 0xc000
	ds_read_b128 v[202:205], v172
	ds_read_b128 v[206:209], v172 offset:1024
	ds_read_b128 v[216:219], v172 offset:2048
	ds_read_b128 v[220:223], v172 offset:3072
	ds_read_b128 v[224:227], v172 offset:4096
	ds_read_b128 v[228:231], v172 offset:5120
	ds_read_b128 v[232:235], v172 offset:6144
	ds_read_b128 v[236:239], v172 offset:7168
	global_load_lds_dwordx4 v[162:163], off
	v_lshl_add_u64 v[162:163], s[28:29], 0, v[156:157]
	s_add_i32 m0, s43, 0xe000
	s_nop 0
	global_load_lds_dwordx4 v[162:163], off
	s_waitcnt vmcnt(8)
	s_waitcnt lgkmcnt(0)
	s_barrier
	s_setprio 1
	s_waitcnt lgkmcnt(0)
	v_mfma_f32_16x16x32_bf16 v[126:129], v[130:133], v[202:205], v[126:129]
	v_mfma_f32_16x16x32_bf16 v[122:125], v[138:141], v[202:205], v[122:125]
	v_mfma_f32_16x16x32_bf16 v[110:113], v[130:133], v[216:219], v[110:113]
	v_mfma_f32_16x16x32_bf16 v[106:109], v[138:141], v[216:219], v[106:109]
	v_mfma_f32_16x16x32_bf16 v[94:97], v[130:133], v[224:227], v[94:97]
	v_mfma_f32_16x16x32_bf16 v[90:93], v[138:141], v[224:227], v[90:93]
	v_mfma_f32_16x16x32_bf16 v[76:79], v[130:133], v[232:235], v[76:79]
	v_mfma_f32_16x16x32_bf16 v[72:75], v[138:141], v[232:235], v[72:75]
	v_mfma_f32_16x16x32_bf16 v[126:129], v[134:137], v[206:209], v[126:129]
	v_mfma_f32_16x16x32_bf16 v[122:125], v[142:145], v[206:209], v[122:125]
	v_mfma_f32_16x16x32_bf16 v[110:113], v[134:137], v[220:223], v[110:113]
	v_mfma_f32_16x16x32_bf16 v[106:109], v[142:145], v[220:223], v[106:109]
	v_mfma_f32_16x16x32_bf16 v[94:97], v[134:137], v[228:231], v[94:97]
	v_mfma_f32_16x16x32_bf16 v[90:93], v[142:145], v[228:231], v[90:93]
	v_mfma_f32_16x16x32_bf16 v[76:79], v[134:137], v[236:239], v[76:79]
	v_mfma_f32_16x16x32_bf16 v[72:75], v[142:145], v[236:239], v[72:75]
	v_mfma_f32_16x16x32_bf16 v[118:121], v[158:161], v[202:205], v[118:121]
	v_mfma_f32_16x16x32_bf16 v[114:117], v[178:181], v[202:205], v[114:117]
	v_mfma_f32_16x16x32_bf16 v[102:105], v[158:161], v[216:219], v[102:105]
	v_mfma_f32_16x16x32_bf16 v[98:101], v[178:181], v[216:219], v[98:101]
	v_mfma_f32_16x16x32_bf16 v[86:89], v[158:161], v[224:227], v[86:89]
	v_mfma_f32_16x16x32_bf16 v[82:85], v[178:181], v[224:227], v[82:85]
	v_mfma_f32_16x16x32_bf16 v[68:71], v[158:161], v[232:235], v[68:71]
	v_mfma_f32_16x16x32_bf16 v[64:67], v[178:181], v[232:235], v[64:67]
	v_mfma_f32_16x16x32_bf16 v[118:121], v[174:177], v[206:209], v[118:121]
	v_mfma_f32_16x16x32_bf16 v[114:117], v[198:201], v[206:209], v[114:117]
	v_mfma_f32_16x16x32_bf16 v[102:105], v[174:177], v[220:223], v[102:105]
	v_mfma_f32_16x16x32_bf16 v[98:101], v[198:201], v[220:223], v[98:101]
	v_mfma_f32_16x16x32_bf16 v[86:89], v[174:177], v[228:231], v[86:89]
	v_mfma_f32_16x16x32_bf16 v[82:85], v[198:201], v[228:231], v[82:85]
	v_mfma_f32_16x16x32_bf16 v[68:71], v[174:177], v[236:239], v[68:71]
	v_mfma_f32_16x16x32_bf16 v[64:67], v[198:201], v[236:239], v[64:67]
	s_setprio 0
	s_barrier
	s_add_i32 s75, s75, s31
	v_lshl_add_u64 v[162:163], s[40:41], 0, v[148:149]
	s_mov_b32 m0, s75
	ds_read_b128 v[202:205], v172 offset:16384
	ds_read_b128 v[206:209], v172 offset:17408
	ds_read_b128 v[216:219], v172 offset:18432
	ds_read_b128 v[220:223], v172 offset:19456
	ds_read_b128 v[224:227], v172 offset:20480
	ds_read_b128 v[228:231], v172 offset:21504
	ds_read_b128 v[232:235], v172 offset:22528
	ds_read_b128 v[236:239], v172 offset:23552
	global_load_lds_dwordx4 v[162:163], off
	s_add_i32 m0, s75, 0x2000
	s_add_u32 s76, s40, 0x40000
	v_lshl_add_u64 v[240:241], s[40:41], 0, v[152:153]
	s_addc_u32 s77, s41, 0
	s_add_i32 s75, s78, s31
	global_load_lds_dwordx4 v[240:241], off
	v_lshl_add_u64 v[242:243], s[76:77], 0, v[148:149]
	s_mov_b32 m0, s75
	v_lshl_add_u64 v[244:245], s[60:61], 0, v[150:151]
	global_load_lds_dwordx4 v[242:243], off
	v_lshl_add_u64 v[242:243], s[76:77], 0, v[152:153]
	s_add_i32 m0, s75, 0x2000
	s_nop 0
	global_load_lds_dwordx4 v[242:243], off
	v_lshl_add_u64 v[242:243], s[60:61], 0, v[146:147]
	s_mov_b32 m0, s43
	s_nop 0
	global_load_lds_dwordx4 v[242:243], off
	s_mov_b32 m0, s62
	s_nop 0
	global_load_lds_dwordx4 v[244:245], off
	s_waitcnt vmcnt(8)
	s_waitcnt lgkmcnt(0)
	s_barrier
; #define PG8_STAGE(bufoff, gbase, voff) do { _Pragma("unroll") for (int _i = 0; _i < 2; ++_i) \
;         __builtin_amdgcn_global_load_lds((const unsigned*)((const char*)(gbase) + (voff)[_i]), (LAS unsigned*)(lds + (bufoff) + ldsw + _i * 8192), 16, 0, 0); } while (0)
; #define PG8_LDA(dst, b, h) do { _Pragma("unroll") for (int m = 0; m < 4; ++m) _Pragma("unroll") for (int k = 0; k < 2; ++k) dst[m][k] = *(const LAS bf16x8*)(lds + PG8_SA(b, h) + aoff + m * 2048 + k * 1024); } while (0)
; #define PG8_LDB(dst, b, h) do { _Pragma("unroll") for (int n = 0; n < 2; ++n) _Pragma("unroll") for (int k = 0; k < 2; ++k) dst[n][k] = *(const LAS bf16x8*)(lds + PG8_SB(b, h) + boff + n * 2048 + k * 1024); } while (0)
; #define PG8_MMA(ai, bj, At, Bt) do { __builtin_amdgcn_s_setprio(1); _Pragma("unroll") for (int m = 0; m < 4; ++m) _Pragma("unroll") for (int n = 0; n < 2; ++n) _Pragma("unroll") for (int k = 0; k < 2; ++k) \
;         acc[ai][bj][m][n] = MFMA16(Bt[n][k], At[m][k], acc[ai][bj][m][n]); __builtin_amdgcn_s_setprio(0); } while (0)
; #define PG8_WAIT_V(n) asm volatile("s_waitcnt vmcnt(" #n ")" ::: "memory")
; #define PG8_WAIT_L(n) asm volatile("s_waitcnt lgkmcnt(" #n ")" ::: "memory")
; #define PG8_BAR __builtin_amdgcn_s_barrier()
; #define PG8_SCHED __builtin_amdgcn_sched_barrier(0)
; template <class Epi>
; __device__ __forceinline__ void gemm_phase(LAS unsigned char* lds, const Gemm g, const StaticOrder& S, const Epi& E, int tid_) {
;     ...
;             PG8_WAIT_V(8); PG8_WAIT_L(0); PG8_BAR; PG8_MMA(1, 0, At, B0); PG8_MMA(1, 1, At, B1); PG8_BAR; PG8_SCHED;
;             PG8_LDB(B0, 1, 0); PG8_LDB(B1, 1, 1); PG8_SCHED; PG8_LDA(At, 1, 0); PG8_STAGE(PG8_SA(0, 1), a2 + hsA, voffA);
;             PG8_WAIT_V(8); PG8_WAIT_L(0); PG8_BAR; PG8_MMA(0, 0, At, B0); PG8_MMA(0, 1, At, B1); PG8_BAR; PG8_SCHED;
	s_setprio 1
	s_waitcnt lgkmcnt(0)
	v_mfma_f32_16x16x32_bf16 v[60:63], v[130:133], v[202:205], v[60:63]
	v_mfma_f32_16x16x32_bf16 v[56:59], v[138:141], v[202:205], v[56:59]
	v_mfma_f32_16x16x32_bf16 v[44:47], v[130:133], v[216:219], v[44:47]
	v_mfma_f32_16x16x32_bf16 v[40:43], v[138:141], v[216:219], v[40:43]
	v_mfma_f32_16x16x32_bf16 v[28:31], v[130:133], v[224:227], v[28:31]
	v_mfma_f32_16x16x32_bf16 v[24:27], v[138:141], v[224:227], v[24:27]
	v_mfma_f32_16x16x32_bf16 v[12:15], v[130:133], v[232:235], v[12:15]
	v_mfma_f32_16x16x32_bf16 v[8:11], v[138:141], v[232:235], v[8:11]
	v_mfma_f32_16x16x32_bf16 v[60:63], v[134:137], v[206:209], v[60:63]
	v_mfma_f32_16x16x32_bf16 v[56:59], v[142:145], v[206:209], v[56:59]
	v_mfma_f32_16x16x32_bf16 v[44:47], v[134:137], v[220:223], v[44:47]
	v_mfma_f32_16x16x32_bf16 v[40:43], v[142:145], v[220:223], v[40:43]
	v_mfma_f32_16x16x32_bf16 v[28:31], v[134:137], v[228:231], v[28:31]
	v_mfma_f32_16x16x32_bf16 v[24:27], v[142:145], v[228:231], v[24:27]
	v_mfma_f32_16x16x32_bf16 v[12:15], v[134:137], v[236:239], v[12:15]
	v_mfma_f32_16x16x32_bf16 v[8:11], v[142:145], v[236:239], v[8:11]
	v_mfma_f32_16x16x32_bf16 v[52:55], v[158:161], v[202:205], v[52:55]
	v_mfma_f32_16x16x32_bf16 v[48:51], v[178:181], v[202:205], v[48:51]
	v_mfma_f32_16x16x32_bf16 v[36:39], v[158:161], v[216:219], v[36:39]
	v_mfma_f32_16x16x32_bf16 v[32:35], v[178:181], v[216:219], v[32:35]
	v_mfma_f32_16x16x32_bf16 v[20:23], v[158:161], v[224:227], v[20:23]
	v_mfma_f32_16x16x32_bf16 v[16:19], v[178:181], v[224:227], v[16:19]
	v_mfma_f32_16x16x32_bf16 v[4:7], v[158:161], v[232:235], v[4:7]
	v_mfma_f32_16x16x32_bf16 v[0:3], v[178:181], v[232:235], v[0:3]
	v_mfma_f32_16x16x32_bf16 v[52:55], v[174:177], v[206:209], v[52:55]
	v_mfma_f32_16x16x32_bf16 v[48:51], v[198:201], v[206:209], v[48:51]
	v_mfma_f32_16x16x32_bf16 v[36:39], v[174:177], v[220:223], v[36:39]
	v_mfma_f32_16x16x32_bf16 v[32:35], v[198:201], v[220:223], v[32:35]
	v_mfma_f32_16x16x32_bf16 v[20:23], v[174:177], v[228:231], v[20:23]
	v_mfma_f32_16x16x32_bf16 v[16:19], v[198:201], v[228:231], v[16:19]
	v_mfma_f32_16x16x32_bf16 v[4:7], v[174:177], v[236:239], v[4:7]
	v_mfma_f32_16x16x32_bf16 v[0:3], v[198:201], v[236:239], v[0:3]
	s_setprio 0
	s_barrier
	s_add_i32 s75, 0, 0x18000
	s_add_i32 s76, 0, 0x1c000
	v_add_u32_e32 v142, s75, v165
	v_add_u32_e32 v173, s76, v165
	ds_read_b128 v[130:133], v142
	ds_read_b128 v[134:137], v142 offset:1024
	ds_read_b128 v[138:141], v142 offset:2048
	ds_read_b128 v[142:145], v142 offset:3072
	ds_read_b128 v[158:161], v173
	ds_read_b128 v[174:177], v173 offset:1024
	ds_read_b128 v[178:181], v173 offset:2048
	ds_read_b128 v[198:201], v173 offset:3072
	s_add_u32 s60, s60, 0x40000
	s_addc_u32 s61, s61, 0
	s_mov_b32 m0, s63
	v_lshl_add_u64 v[246:247], s[60:61], 0, v[146:147]
	ds_read_b128 v[202:205], v172 offset:32768
	ds_read_b128 v[206:209], v172 offset:33792
	ds_read_b128 v[216:219], v172 offset:34816
	ds_read_b128 v[220:223], v172 offset:35840
	ds_read_b128 v[224:227], v172 offset:36864
	ds_read_b128 v[228:231], v172 offset:37888
	ds_read_b128 v[232:235], v172 offset:38912
	ds_read_b128 v[236:239], v172 offset:39936
	global_load_lds_dwordx4 v[246:247], off
	v_lshl_add_u64 v[246:247], s[60:61], 0, v[150:151]
	s_mov_b32 m0, s64
	s_nop 0
	global_load_lds_dwordx4 v[246:247], off
	s_waitcnt vmcnt(8)
	s_waitcnt lgkmcnt(0)
	s_barrier
	s_setprio 1
	s_waitcnt lgkmcnt(0)
	v_mfma_f32_16x16x32_bf16 v[126:129], v[130:133], v[202:205], v[126:129]
	v_mfma_f32_16x16x32_bf16 v[122:125], v[138:141], v[202:205], v[122:125]
	v_mfma_f32_16x16x32_bf16 v[110:113], v[130:133], v[216:219], v[110:113]
	v_mfma_f32_16x16x32_bf16 v[106:109], v[138:141], v[216:219], v[106:109]
	v_mfma_f32_16x16x32_bf16 v[94:97], v[130:133], v[224:227], v[94:97]
	v_mfma_f32_16x16x32_bf16 v[90:93], v[138:141], v[224:227], v[90:93]
	v_mfma_f32_16x16x32_bf16 v[76:79], v[130:133], v[232:235], v[76:79]
	v_mfma_f32_16x16x32_bf16 v[72:75], v[138:141], v[232:235], v[72:75]
	v_mfma_f32_16x16x32_bf16 v[126:129], v[134:137], v[206:209], v[126:129]
	v_mfma_f32_16x16x32_bf16 v[122:125], v[142:145], v[206:209], v[122:125]
	v_mfma_f32_16x16x32_bf16 v[110:113], v[134:137], v[220:223], v[110:113]
	v_mfma_f32_16x16x32_bf16 v[106:109], v[142:145], v[220:223], v[106:109]
	v_mfma_f32_16x16x32_bf16 v[94:97], v[134:137], v[228:231], v[94:97]
	v_mfma_f32_16x16x32_bf16 v[90:93], v[142:145], v[228:231], v[90:93]
	v_mfma_f32_16x16x32_bf16 v[76:79], v[134:137], v[236:239], v[76:79]
	v_mfma_f32_16x16x32_bf16 v[72:75], v[142:145], v[236:239], v[72:75]
	v_mfma_f32_16x16x32_bf16 v[118:121], v[158:161], v[202:205], v[118:121]
	v_mfma_f32_16x16x32_bf16 v[114:117], v[178:181], v[202:205], v[114:117]
	v_mfma_f32_16x16x32_bf16 v[102:105], v[158:161], v[216:219], v[102:105]
	v_mfma_f32_16x16x32_bf16 v[98:101], v[178:181], v[216:219], v[98:101]
	v_mfma_f32_16x16x32_bf16 v[86:89], v[158:161], v[224:227], v[86:89]
	v_mfma_f32_16x16x32_bf16 v[82:85], v[178:181], v[224:227], v[82:85]
	v_mfma_f32_16x16x32_bf16 v[68:71], v[158:161], v[232:235], v[68:71]
	v_mfma_f32_16x16x32_bf16 v[64:67], v[178:181], v[232:235], v[64:67]
	v_mfma_f32_16x16x32_bf16 v[118:121], v[174:177], v[206:209], v[118:121]
	v_mfma_f32_16x16x32_bf16 v[114:117], v[198:201], v[206:209], v[114:117]
	v_mfma_f32_16x16x32_bf16 v[102:105], v[174:177], v[220:223], v[102:105]
	v_mfma_f32_16x16x32_bf16 v[98:101], v[198:201], v[220:223], v[98:101]
	v_mfma_f32_16x16x32_bf16 v[86:89], v[174:177], v[228:231], v[86:89]
	v_mfma_f32_16x16x32_bf16 v[82:85], v[198:201], v[228:231], v[82:85]
	v_mfma_f32_16x16x32_bf16 v[68:71], v[174:177], v[236:239], v[68:71]
	v_mfma_f32_16x16x32_bf16 v[64:67], v[198:201], v[236:239], v[64:67]
	s_setprio 0
	s_barrier
; #define PG8_STAGE(bufoff, gbase, voff) do { _Pragma("unroll") for (int _i = 0; _i < 2; ++_i) \
;         __builtin_amdgcn_global_load_lds((const unsigned*)((const char*)(gbase) + (voff)[_i]), (LAS unsigned*)(lds + (bufoff) + ldsw + _i * 8192), 16, 0, 0); } while (0)
; #define PG8_LDA(dst, b, h) do { _Pragma("unroll") for (int m = 0; m < 4; ++m) _Pragma("unroll") for (int k = 0; k < 2; ++k) dst[m][k] = *(const LAS bf16x8*)(lds + PG8_SA(b, h) + aoff + m * 2048 + k * 1024); } while (0)
; #define PG8_MMA(ai, bj, At, Bt) do { __builtin_amdgcn_s_setprio(1); _Pragma("unroll") for (int m = 0; m < 4; ++m) _Pragma("unroll") for (int n = 0; n < 2; ++n) _Pragma("unroll") for (int k = 0; k < 2; ++k) \
;         acc[ai][bj][m][n] = MFMA16(Bt[n][k], At[m][k], acc[ai][bj][m][n]); __builtin_amdgcn_s_setprio(0); } while (0)
; #define PG8_WAIT_V(n) asm volatile("s_waitcnt vmcnt(" #n ")" ::: "memory")
; #define PG8_WAIT_L(n) asm volatile("s_waitcnt lgkmcnt(" #n ")" ::: "memory")
; #define PG8_BAR __builtin_amdgcn_s_barrier()
; #define PG8_SCHED __builtin_amdgcn_sched_barrier(0)
; template <class Epi>
; __device__ __forceinline__ void gemm_phase(LAS unsigned char* lds, const Gemm g, const StaticOrder& S, const Epi& E, int tid_) {
;     ...
;         for (int t = 0; t < nt; t += 2) {
;     ...
;             PG8_LDA(At, 1, 1); PG8_STAGE(PG8_SB(1, 0), b3, voffB); PG8_STAGE(PG8_SB(1, 1), b3 + hsB, voffB); PG8_STAGE(PG8_SA(1, 0), a3, voffA);
;             PG8_WAIT_V(8); PG8_WAIT_L(0); PG8_BAR; PG8_MMA(1, 0, At, B0); PG8_MMA(1, 1, At, B1); PG8_BAR; PG8_SCHED;
;         }
	s_add_i32 s60, s75, s31
	v_lshl_add_u64 v[162:163], v[162:163], 0, s[6:7]
	s_mov_b32 m0, s60
	ds_read_b128 v[202:205], v172 offset:49152
	ds_read_b128 v[206:209], v172 offset:50176
	ds_read_b128 v[216:219], v172 offset:51200
	ds_read_b128 v[220:223], v172 offset:52224
	ds_read_b128 v[224:227], v172 offset:53248
	ds_read_b128 v[228:231], v172 offset:54272
	ds_read_b128 v[232:235], v172 offset:55296
	ds_read_b128 v[236:239], v172 offset:56320
	global_load_lds_dwordx4 v[162:163], off
	s_add_i32 m0, s60, 0x2000
	s_add_u32 s40, s40, 0x40080
	v_lshl_add_u64 v[162:163], v[240:241], 0, s[6:7]
	s_addc_u32 s41, s41, 0
	s_add_i32 s60, s76, s31
	global_load_lds_dwordx4 v[162:163], off
	v_lshl_add_u64 v[162:163], s[40:41], 0, v[148:149]
	s_mov_b32 m0, s60
	s_nop 0
	global_load_lds_dwordx4 v[162:163], off
	v_lshl_add_u64 v[162:163], s[40:41], 0, v[152:153]
	s_add_i32 m0, s60, 0x2000
	s_nop 0
	global_load_lds_dwordx4 v[162:163], off
	v_lshl_add_u64 v[162:163], v[242:243], 0, s[6:7]
	s_mov_b32 m0, s65
	s_nop 0
	global_load_lds_dwordx4 v[162:163], off
	v_lshl_add_u64 v[162:163], v[244:245], 0, s[6:7]
	s_mov_b32 m0, s66
	s_nop 0
	global_load_lds_dwordx4 v[162:163], off
	s_waitcnt vmcnt(8)
	s_waitcnt lgkmcnt(0)
	s_barrier
	s_setprio 1
	s_waitcnt lgkmcnt(0)
	v_mfma_f32_16x16x32_bf16 v[60:63], v[130:133], v[202:205], v[60:63]
	v_mfma_f32_16x16x32_bf16 v[56:59], v[138:141], v[202:205], v[56:59]
	v_mfma_f32_16x16x32_bf16 v[44:47], v[130:133], v[216:219], v[44:47]
	v_mfma_f32_16x16x32_bf16 v[40:43], v[138:141], v[216:219], v[40:43]
	v_mfma_f32_16x16x32_bf16 v[28:31], v[130:133], v[224:227], v[28:31]
	v_mfma_f32_16x16x32_bf16 v[24:27], v[138:141], v[224:227], v[24:27]
	v_mfma_f32_16x16x32_bf16 v[12:15], v[130:133], v[232:235], v[12:15]
	v_mfma_f32_16x16x32_bf16 v[8:11], v[138:141], v[232:235], v[8:11]
	v_mfma_f32_16x16x32_bf16 v[60:63], v[134:137], v[206:209], v[60:63]
	v_mfma_f32_16x16x32_bf16 v[56:59], v[142:145], v[206:209], v[56:59]
	v_mfma_f32_16x16x32_bf16 v[44:47], v[134:137], v[220:223], v[44:47]
	v_mfma_f32_16x16x32_bf16 v[40:43], v[142:145], v[220:223], v[40:43]
	v_mfma_f32_16x16x32_bf16 v[28:31], v[134:137], v[228:231], v[28:31]
	v_mfma_f32_16x16x32_bf16 v[24:27], v[142:145], v[228:231], v[24:27]
	v_mfma_f32_16x16x32_bf16 v[12:15], v[134:137], v[236:239], v[12:15]
	v_mfma_f32_16x16x32_bf16 v[8:11], v[142:145], v[236:239], v[8:11]
	v_mfma_f32_16x16x32_bf16 v[52:55], v[158:161], v[202:205], v[52:55]
	v_mfma_f32_16x16x32_bf16 v[48:51], v[178:181], v[202:205], v[48:51]
	v_mfma_f32_16x16x32_bf16 v[36:39], v[158:161], v[216:219], v[36:39]
	v_mfma_f32_16x16x32_bf16 v[32:35], v[178:181], v[216:219], v[32:35]
	v_mfma_f32_16x16x32_bf16 v[20:23], v[158:161], v[224:227], v[20:23]
	v_mfma_f32_16x16x32_bf16 v[16:19], v[178:181], v[224:227], v[16:19]
	v_mfma_f32_16x16x32_bf16 v[4:7], v[158:161], v[232:235], v[4:7]
	v_mfma_f32_16x16x32_bf16 v[0:3], v[178:181], v[232:235], v[0:3]
	v_mfma_f32_16x16x32_bf16 v[52:55], v[174:177], v[206:209], v[52:55]
	v_mfma_f32_16x16x32_bf16 v[48:51], v[198:201], v[206:209], v[48:51]
	v_mfma_f32_16x16x32_bf16 v[36:39], v[174:177], v[220:223], v[36:39]
	v_mfma_f32_16x16x32_bf16 v[32:35], v[198:201], v[220:223], v[32:35]
	v_mfma_f32_16x16x32_bf16 v[20:23], v[174:177], v[228:231], v[20:23]
	v_mfma_f32_16x16x32_bf16 v[16:19], v[198:201], v[228:231], v[16:19]
	v_mfma_f32_16x16x32_bf16 v[4:7], v[174:177], v[236:239], v[4:7]
	v_mfma_f32_16x16x32_bf16 v[0:3], v[198:201], v[236:239], v[0:3]
	s_setprio 0
	s_barrier
	s_add_u32 s28, s28, 0x100
	s_addc_u32 s29, s29, 0
	s_add_u32 s72, s72, 0x100
	s_addc_u32 s73, s73, 0
	s_cmp_ge_i32 s74, s18
	s_mov_b32 s40, s74
	s_cbranch_scc0 .LBB0_172
	s_and_b64 vcc, exec, s[52:53]
	s_cbranch_vccz .LBB0_175

; #define PG8_STAGE(bufoff, gbase, voff) do { _Pragma("unroll") for (int _i = 0; _i < 2; ++_i) \
;         __builtin_amdgcn_global_load_lds((const unsigned*)((const char*)(gbase) + (voff)[_i]), (LAS unsigned*)(lds + (bufoff) + ldsw + _i * 8192), 16, 0, 0); } while (0)
; #define PG8_LDA(dst, b, h) do { _Pragma("unroll") for (int m = 0; m < 4; ++m) _Pragma("unroll") for (int k = 0; k < 2; ++k) dst[m][k] = *(const LAS bf16x8*)(lds + PG8_SA(b, h) + aoff + m * 2048 + k * 1024); } while (0)
; #define PG8_LDB(dst, b, h) do { _Pragma("unroll") for (int n = 0; n < 2; ++n) _Pragma("unroll") for (int k = 0; k < 2; ++k) dst[n][k] = *(const LAS bf16x8*)(lds + PG8_SB(b, h) + boff + n * 2048 + k * 1024); } while (0)
; #define PG8_MMA(ai, bj, At, Bt) do { __builtin_amdgcn_s_setprio(1); _Pragma("unroll") for (int m = 0; m < 4; ++m) _Pragma("unroll") for (int n = 0; n < 2; ++n) _Pragma("unroll") for (int k = 0; k < 2; ++k) \
;         acc[ai][bj][m][n] = MFMA16(Bt[n][k], At[m][k], acc[ai][bj][m][n]); __builtin_amdgcn_s_setprio(0); } while (0)
; #define PG8_WAIT_V(n) asm volatile("s_waitcnt vmcnt(" #n ")" ::: "memory")
; #define PG8_WAIT_L(n) asm volatile("s_waitcnt lgkmcnt(" #n ")" ::: "memory")
; #define PG8_BAR __builtin_amdgcn_s_barrier()
; #define PG8_SCHED __builtin_amdgcn_sched_barrier(0)
; template <class Epi>
; __device__ __forceinline__ void gemm_phase(LAS unsigned char* lds, const Gemm g, const StaticOrder& S, const Epi& E, int tid_) {
;     ...
;             const bool last = (t == nt - 2);
;             const char* a1 = cA + (size_t)(t + 1) * kstep;
;             const char* a2 = last ? nA : cA + (size_t)(t + 2) * kstep; const char* b2 = last ? nB : cB + (size_t)(t + 2) * kstep;
;             const char* a3 = a2 + kstep; const char* b3 = b2 + kstep;
;             PG8_LDB(B0, 0, 0); PG8_LDB(B1, 0, 1); PG8_SCHED; PG8_LDA(At, 0, 0); PG8_STAGE(PG8_SA(1, 1), a1 + hsA, voffA);
;             PG8_WAIT_V(8); PG8_WAIT_L(0); PG8_BAR; PG8_MMA(0, 0, At, B0); PG8_MMA(0, 1, At, B1); PG8_BAR; PG8_SCHED;
;             PG8_LDA(At, 0, 1); PG8_STAGE(PG8_SB(0, 0), b2, voffB); PG8_STAGE(PG8_SB(0, 1), b2 + hsB, voffB); PG8_STAGE(PG8_SA(0, 0), a2, voffA);
;             PG8_WAIT_V(8); PG8_WAIT_L(0); PG8_BAR; PG8_MMA(1, 0, At, B0); PG8_MMA(1, 1, At, B1); PG8_BAR; PG8_SCHED;
.LBB0_320:
	s_add_i32 s81, s66, 2
	s_add_u32 s67, s64, 0xfffc0080
	s_addc_u32 s68, s65, -1
	s_add_i32 s82, 0, 0x10000
	s_cmp_eq_u32 s78, s66
	s_cselect_b32 s69, s22, s68
	s_cselect_b32 s68, s23, s67
	s_cselect_b32 s67, s29, s80
	s_cselect_b32 s66, s57, s59
	s_add_i32 s91, 0, 0x14000
	v_add_u32_e32 v94, s82, v81
	v_add_u32_e32 v150, s91, v81
	ds_read_b128 v[76:79], v94
	ds_read_b128 v[82:85], v94 offset:1024
	ds_read_b128 v[90:93], v94 offset:2048
	ds_read_b128 v[94:97], v94 offset:3072
	ds_read_b128 v[98:101], v150
	ds_read_b128 v[114:117], v150 offset:1024
	ds_read_b128 v[134:137], v150 offset:2048
	ds_read_b128 v[150:153], v150 offset:3072
	v_lshl_add_u64 v[232:233], s[64:65], 0, v[206:207]
	s_add_i32 m0, s72, 0xc000
	ds_read_b128 v[162:165], v218
	ds_read_b128 v[166:169], v218 offset:1024
	ds_read_b128 v[170:173], v218 offset:2048
	ds_read_b128 v[174:177], v218 offset:3072
	ds_read_b128 v[178:181], v218 offset:4096
	ds_read_b128 v[220:223], v218 offset:5120
	ds_read_b128 v[224:227], v218 offset:6144
	ds_read_b128 v[228:231], v218 offset:7168
	global_load_lds_dwordx4 v[232:233], off
	v_lshl_add_u64 v[232:233], s[64:65], 0, v[208:209]
	s_add_i32 m0, s72, 0xe000
	s_nop 0
	global_load_lds_dwordx4 v[232:233], off
	s_waitcnt vmcnt(8)
	s_waitcnt lgkmcnt(0)
	s_barrier
	s_setprio 1
	s_waitcnt lgkmcnt(0)
	v_mfma_f32_16x16x32_bf16 v[158:161], v[76:79], v[162:165], v[158:161]
	v_mfma_f32_16x16x32_bf16 v[146:149], v[90:93], v[162:165], v[146:149]
	v_mfma_f32_16x16x32_bf16 v[138:141], v[76:79], v[170:173], v[138:141]
	v_mfma_f32_16x16x32_bf16 v[126:129], v[90:93], v[170:173], v[126:129]
	v_mfma_f32_16x16x32_bf16 v[118:121], v[76:79], v[178:181], v[118:121]
	v_mfma_f32_16x16x32_bf16 v[106:109], v[90:93], v[178:181], v[106:109]
	v_mfma_f32_16x16x32_bf16 v[86:89], v[76:79], v[224:227], v[86:89]
	v_mfma_f32_16x16x32_bf16 v[68:71], v[90:93], v[224:227], v[68:71]
	v_mfma_f32_16x16x32_bf16 v[158:161], v[82:85], v[166:169], v[158:161]
	v_mfma_f32_16x16x32_bf16 v[146:149], v[94:97], v[166:169], v[146:149]
	v_mfma_f32_16x16x32_bf16 v[138:141], v[82:85], v[174:177], v[138:141]
	v_mfma_f32_16x16x32_bf16 v[126:129], v[94:97], v[174:177], v[126:129]
	v_mfma_f32_16x16x32_bf16 v[118:121], v[82:85], v[220:223], v[118:121]
	v_mfma_f32_16x16x32_bf16 v[106:109], v[94:97], v[220:223], v[106:109]
	v_mfma_f32_16x16x32_bf16 v[86:89], v[82:85], v[228:231], v[86:89]
	v_mfma_f32_16x16x32_bf16 v[68:71], v[94:97], v[228:231], v[68:71]
	v_mfma_f32_16x16x32_bf16 v[154:157], v[98:101], v[162:165], v[154:157]
	v_mfma_f32_16x16x32_bf16 v[142:145], v[134:137], v[162:165], v[142:145]
	v_mfma_f32_16x16x32_bf16 v[130:133], v[98:101], v[170:173], v[130:133]
	v_mfma_f32_16x16x32_bf16 v[122:125], v[134:137], v[170:173], v[122:125]
	v_mfma_f32_16x16x32_bf16 v[110:113], v[98:101], v[178:181], v[110:113]
	v_mfma_f32_16x16x32_bf16 v[102:105], v[134:137], v[178:181], v[102:105]
	v_mfma_f32_16x16x32_bf16 v[72:75], v[98:101], v[224:227], v[72:75]
	v_mfma_f32_16x16x32_bf16 v[64:67], v[134:137], v[224:227], v[64:67]
	v_mfma_f32_16x16x32_bf16 v[154:157], v[114:117], v[166:169], v[154:157]
	v_mfma_f32_16x16x32_bf16 v[142:145], v[150:153], v[166:169], v[142:145]
	v_mfma_f32_16x16x32_bf16 v[130:133], v[114:117], v[174:177], v[130:133]
	v_mfma_f32_16x16x32_bf16 v[122:125], v[150:153], v[174:177], v[122:125]
	v_mfma_f32_16x16x32_bf16 v[110:113], v[114:117], v[220:223], v[110:113]
	v_mfma_f32_16x16x32_bf16 v[102:105], v[150:153], v[220:223], v[102:105]
	v_mfma_f32_16x16x32_bf16 v[72:75], v[114:117], v[228:231], v[72:75]
	v_mfma_f32_16x16x32_bf16 v[64:67], v[150:153], v[228:231], v[64:67]
	s_setprio 0
	s_barrier
	s_add_i32 s82, s82, s31
	v_lshl_add_u64 v[232:233], s[66:67], 0, v[200:201]
	s_mov_b32 m0, s82
	ds_read_b128 v[162:165], v218 offset:16384
	ds_read_b128 v[166:169], v218 offset:17408
	ds_read_b128 v[170:173], v218 offset:18432
	ds_read_b128 v[174:177], v218 offset:19456
	ds_read_b128 v[178:181], v218 offset:20480
	ds_read_b128 v[220:223], v218 offset:21504
	ds_read_b128 v[224:227], v218 offset:22528
	ds_read_b128 v[228:231], v218 offset:23552
	global_load_lds_dwordx4 v[232:233], off
	s_add_i32 m0, s82, 0x2000
	s_add_u32 s82, s66, 0x8000
	v_lshl_add_u64 v[234:235], s[66:67], 0, v[204:205]
	s_addc_u32 s83, s67, 0
	s_add_i32 s91, s91, s31
	global_load_lds_dwordx4 v[234:235], off
	v_lshl_add_u64 v[236:237], s[82:83], 0, v[200:201]
	s_mov_b32 m0, s91
	v_lshl_add_u64 v[238:239], s[68:69], 0, v[202:203]
	global_load_lds_dwordx4 v[236:237], off
	v_lshl_add_u64 v[236:237], s[82:83], 0, v[204:205]
	s_add_i32 m0, s91, 0x2000
	s_nop 0
	global_load_lds_dwordx4 v[236:237], off
	v_lshl_add_u64 v[236:237], s[68:69], 0, v[198:199]
	s_mov_b32 m0, s72
	s_nop 0
	global_load_lds_dwordx4 v[236:237], off
	s_mov_b32 m0, s73
	s_nop 0
	global_load_lds_dwordx4 v[238:239], off
	s_waitcnt vmcnt(8)
	s_waitcnt lgkmcnt(0)
	s_barrier
; #define PG8_STAGE(bufoff, gbase, voff) do { _Pragma("unroll") for (int _i = 0; _i < 2; ++_i) \
;         __builtin_amdgcn_global_load_lds((const unsigned*)((const char*)(gbase) + (voff)[_i]), (LAS unsigned*)(lds + (bufoff) + ldsw + _i * 8192), 16, 0, 0); } while (0)
; #define PG8_LDA(dst, b, h) do { _Pragma("unroll") for (int m = 0; m < 4; ++m) _Pragma("unroll") for (int k = 0; k < 2; ++k) dst[m][k] = *(const LAS bf16x8*)(lds + PG8_SA(b, h) + aoff + m * 2048 + k * 1024); } while (0)
; #define PG8_LDB(dst, b, h) do { _Pragma("unroll") for (int n = 0; n < 2; ++n) _Pragma("unroll") for (int k = 0; k < 2; ++k) dst[n][k] = *(const LAS bf16x8*)(lds + PG8_SB(b, h) + boff + n * 2048 + k * 1024); } while (0)
; #define PG8_MMA(ai, bj, At, Bt) do { __builtin_amdgcn_s_setprio(1); _Pragma("unroll") for (int m = 0; m < 4; ++m) _Pragma("unroll") for (int n = 0; n < 2; ++n) _Pragma("unroll") for (int k = 0; k < 2; ++k) \
;         acc[ai][bj][m][n] = MFMA16(Bt[n][k], At[m][k], acc[ai][bj][m][n]); __builtin_amdgcn_s_setprio(0); } while (0)
; #define PG8_WAIT_V(n) asm volatile("s_waitcnt vmcnt(" #n ")" ::: "memory")
; #define PG8_WAIT_L(n) asm volatile("s_waitcnt lgkmcnt(" #n ")" ::: "memory")
; #define PG8_BAR __builtin_amdgcn_s_barrier()
; #define PG8_SCHED __builtin_amdgcn_sched_barrier(0)
; template <class Epi>
; __device__ __forceinline__ void gemm_phase(LAS unsigned char* lds, const Gemm g, const StaticOrder& S, const Epi& E, int tid_) {
;     ...
;             PG8_WAIT_V(8); PG8_WAIT_L(0); PG8_BAR; PG8_MMA(1, 0, At, B0); PG8_MMA(1, 1, At, B1); PG8_BAR; PG8_SCHED;
;             PG8_LDB(B0, 1, 0); PG8_LDB(B1, 1, 1); PG8_SCHED; PG8_LDA(At, 1, 0); PG8_STAGE(PG8_SA(0, 1), a2 + hsA, voffA);
;             PG8_WAIT_V(8); PG8_WAIT_L(0); PG8_BAR; PG8_MMA(0, 0, At, B0); PG8_MMA(0, 1, At, B1); PG8_BAR; PG8_SCHED;
	s_setprio 1
	s_waitcnt lgkmcnt(0)
	v_mfma_f32_16x16x32_bf16 v[60:63], v[76:79], v[162:165], v[60:63]
	v_mfma_f32_16x16x32_bf16 v[52:55], v[90:93], v[162:165], v[52:55]
	v_mfma_f32_16x16x32_bf16 v[44:47], v[76:79], v[170:173], v[44:47]
	v_mfma_f32_16x16x32_bf16 v[36:39], v[90:93], v[170:173], v[36:39]
	v_mfma_f32_16x16x32_bf16 v[28:31], v[76:79], v[178:181], v[28:31]
	v_mfma_f32_16x16x32_bf16 v[20:23], v[90:93], v[178:181], v[20:23]
	v_mfma_f32_16x16x32_bf16 v[12:15], v[76:79], v[224:227], v[12:15]
	v_mfma_f32_16x16x32_bf16 v[4:7], v[90:93], v[224:227], v[4:7]
	v_mfma_f32_16x16x32_bf16 v[60:63], v[82:85], v[166:169], v[60:63]
	v_mfma_f32_16x16x32_bf16 v[52:55], v[94:97], v[166:169], v[52:55]
	v_mfma_f32_16x16x32_bf16 v[44:47], v[82:85], v[174:177], v[44:47]
	v_mfma_f32_16x16x32_bf16 v[36:39], v[94:97], v[174:177], v[36:39]
	v_mfma_f32_16x16x32_bf16 v[28:31], v[82:85], v[220:223], v[28:31]
	v_mfma_f32_16x16x32_bf16 v[20:23], v[94:97], v[220:223], v[20:23]
	v_mfma_f32_16x16x32_bf16 v[12:15], v[82:85], v[228:231], v[12:15]
	v_mfma_f32_16x16x32_bf16 v[4:7], v[94:97], v[228:231], v[4:7]
	v_mfma_f32_16x16x32_bf16 v[56:59], v[98:101], v[162:165], v[56:59]
	v_mfma_f32_16x16x32_bf16 v[48:51], v[134:137], v[162:165], v[48:51]
	v_mfma_f32_16x16x32_bf16 v[40:43], v[98:101], v[170:173], v[40:43]
	v_mfma_f32_16x16x32_bf16 v[32:35], v[134:137], v[170:173], v[32:35]
	v_mfma_f32_16x16x32_bf16 v[24:27], v[98:101], v[178:181], v[24:27]
	v_mfma_f32_16x16x32_bf16 v[16:19], v[134:137], v[178:181], v[16:19]
	v_mfma_f32_16x16x32_bf16 v[8:11], v[98:101], v[224:227], v[8:11]
	v_mfma_f32_16x16x32_bf16 v[0:3], v[134:137], v[224:227], v[0:3]
	v_mfma_f32_16x16x32_bf16 v[56:59], v[114:117], v[166:169], v[56:59]
	v_mfma_f32_16x16x32_bf16 v[48:51], v[150:153], v[166:169], v[48:51]
	v_mfma_f32_16x16x32_bf16 v[40:43], v[114:117], v[174:177], v[40:43]
	v_mfma_f32_16x16x32_bf16 v[32:35], v[150:153], v[174:177], v[32:35]
	v_mfma_f32_16x16x32_bf16 v[24:27], v[114:117], v[220:223], v[24:27]
	v_mfma_f32_16x16x32_bf16 v[16:19], v[150:153], v[220:223], v[16:19]
	v_mfma_f32_16x16x32_bf16 v[8:11], v[114:117], v[228:231], v[8:11]
	v_mfma_f32_16x16x32_bf16 v[0:3], v[150:153], v[228:231], v[0:3]
	s_setprio 0
	s_barrier
	s_add_i32 s82, 0, 0x18000
	s_add_i32 s83, 0, 0x1c000
	v_add_u32_e32 v94, s82, v81
	v_add_u32_e32 v150, s83, v81
	ds_read_b128 v[76:79], v94
	ds_read_b128 v[82:85], v94 offset:1024
	ds_read_b128 v[90:93], v94 offset:2048
	ds_read_b128 v[94:97], v94 offset:3072
	ds_read_b128 v[98:101], v150
	ds_read_b128 v[114:117], v150 offset:1024
	ds_read_b128 v[134:137], v150 offset:2048
	ds_read_b128 v[150:153], v150 offset:3072
	s_add_u32 s68, s68, 0x40000
	s_addc_u32 s69, s69, 0
	s_mov_b32 m0, s74
	v_lshl_add_u64 v[240:241], s[68:69], 0, v[198:199]
	ds_read_b128 v[162:165], v218 offset:32768
	ds_read_b128 v[166:169], v218 offset:33792
	ds_read_b128 v[170:173], v218 offset:34816
	ds_read_b128 v[174:177], v218 offset:35840
	ds_read_b128 v[178:181], v218 offset:36864
	ds_read_b128 v[220:223], v218 offset:37888
	ds_read_b128 v[224:227], v218 offset:38912
	ds_read_b128 v[228:231], v218 offset:39936
	global_load_lds_dwordx4 v[240:241], off
	v_lshl_add_u64 v[240:241], s[68:69], 0, v[202:203]
	s_mov_b32 m0, s75
	s_nop 0
	global_load_lds_dwordx4 v[240:241], off
	s_waitcnt vmcnt(8)
	s_waitcnt lgkmcnt(0)
	s_barrier
	s_setprio 1
	s_waitcnt lgkmcnt(0)
	v_mfma_f32_16x16x32_bf16 v[158:161], v[76:79], v[162:165], v[158:161]
	v_mfma_f32_16x16x32_bf16 v[146:149], v[90:93], v[162:165], v[146:149]
	v_mfma_f32_16x16x32_bf16 v[138:141], v[76:79], v[170:173], v[138:141]
	v_mfma_f32_16x16x32_bf16 v[126:129], v[90:93], v[170:173], v[126:129]
	v_mfma_f32_16x16x32_bf16 v[118:121], v[76:79], v[178:181], v[118:121]
	v_mfma_f32_16x16x32_bf16 v[106:109], v[90:93], v[178:181], v[106:109]
	v_mfma_f32_16x16x32_bf16 v[86:89], v[76:79], v[224:227], v[86:89]
	v_mfma_f32_16x16x32_bf16 v[68:71], v[90:93], v[224:227], v[68:71]
	v_mfma_f32_16x16x32_bf16 v[158:161], v[82:85], v[166:169], v[158:161]
	v_mfma_f32_16x16x32_bf16 v[146:149], v[94:97], v[166:169], v[146:149]
	v_mfma_f32_16x16x32_bf16 v[138:141], v[82:85], v[174:177], v[138:141]
	v_mfma_f32_16x16x32_bf16 v[126:129], v[94:97], v[174:177], v[126:129]
	v_mfma_f32_16x16x32_bf16 v[118:121], v[82:85], v[220:223], v[118:121]
	v_mfma_f32_16x16x32_bf16 v[106:109], v[94:97], v[220:223], v[106:109]
	v_mfma_f32_16x16x32_bf16 v[86:89], v[82:85], v[228:231], v[86:89]
	v_mfma_f32_16x16x32_bf16 v[68:71], v[94:97], v[228:231], v[68:71]
	v_mfma_f32_16x16x32_bf16 v[154:157], v[98:101], v[162:165], v[154:157]
	v_mfma_f32_16x16x32_bf16 v[142:145], v[134:137], v[162:165], v[142:145]
	v_mfma_f32_16x16x32_bf16 v[130:133], v[98:101], v[170:173], v[130:133]
	v_mfma_f32_16x16x32_bf16 v[122:125], v[134:137], v[170:173], v[122:125]
	v_mfma_f32_16x16x32_bf16 v[110:113], v[98:101], v[178:181], v[110:113]
	v_mfma_f32_16x16x32_bf16 v[102:105], v[134:137], v[178:181], v[102:105]
	v_mfma_f32_16x16x32_bf16 v[72:75], v[98:101], v[224:227], v[72:75]
	v_mfma_f32_16x16x32_bf16 v[64:67], v[134:137], v[224:227], v[64:67]
	v_mfma_f32_16x16x32_bf16 v[154:157], v[114:117], v[166:169], v[154:157]
	v_mfma_f32_16x16x32_bf16 v[142:145], v[150:153], v[166:169], v[142:145]
	v_mfma_f32_16x16x32_bf16 v[130:133], v[114:117], v[174:177], v[130:133]
	v_mfma_f32_16x16x32_bf16 v[122:125], v[150:153], v[174:177], v[122:125]
	v_mfma_f32_16x16x32_bf16 v[110:113], v[114:117], v[220:223], v[110:113]
	v_mfma_f32_16x16x32_bf16 v[102:105], v[150:153], v[220:223], v[102:105]
	v_mfma_f32_16x16x32_bf16 v[72:75], v[114:117], v[228:231], v[72:75]
	v_mfma_f32_16x16x32_bf16 v[64:67], v[150:153], v[228:231], v[64:67]
	s_setprio 0
	s_barrier
; #define PG8_STAGE(bufoff, gbase, voff) do { _Pragma("unroll") for (int _i = 0; _i < 2; ++_i) \
;         __builtin_amdgcn_global_load_lds((const unsigned*)((const char*)(gbase) + (voff)[_i]), (LAS unsigned*)(lds + (bufoff) + ldsw + _i * 8192), 16, 0, 0); } while (0)
; #define PG8_LDA(dst, b, h) do { _Pragma("unroll") for (int m = 0; m < 4; ++m) _Pragma("unroll") for (int k = 0; k < 2; ++k) dst[m][k] = *(const LAS bf16x8*)(lds + PG8_SA(b, h) + aoff + m * 2048 + k * 1024); } while (0)
; #define PG8_MMA(ai, bj, At, Bt) do { __builtin_amdgcn_s_setprio(1); _Pragma("unroll") for (int m = 0; m < 4; ++m) _Pragma("unroll") for (int n = 0; n < 2; ++n) _Pragma("unroll") for (int k = 0; k < 2; ++k) \
;         acc[ai][bj][m][n] = MFMA16(Bt[n][k], At[m][k], acc[ai][bj][m][n]); __builtin_amdgcn_s_setprio(0); } while (0)
; #define PG8_WAIT_V(n) asm volatile("s_waitcnt vmcnt(" #n ")" ::: "memory")
; #define PG8_WAIT_L(n) asm volatile("s_waitcnt lgkmcnt(" #n ")" ::: "memory")
; #define PG8_BAR __builtin_amdgcn_s_barrier()
; #define PG8_SCHED __builtin_amdgcn_sched_barrier(0)
; template <class Epi>
; __device__ __forceinline__ void gemm_phase(LAS unsigned char* lds, const Gemm g, const StaticOrder& S, const Epi& E, int tid_) {
;     ...
;         for (int t = 0; t < nt; t += 2) {
;     ...
;             PG8_LDA(At, 1, 1); PG8_STAGE(PG8_SB(1, 0), b3, voffB); PG8_STAGE(PG8_SB(1, 1), b3 + hsB, voffB); PG8_STAGE(PG8_SA(1, 0), a3, voffA);
;             PG8_WAIT_V(8); PG8_WAIT_L(0); PG8_BAR; PG8_MMA(1, 0, At, B0); PG8_MMA(1, 1, At, B1); PG8_BAR; PG8_SCHED;
;         }
	s_add_i32 s68, s82, s31
	v_lshl_add_u64 v[232:233], v[232:233], 0, s[6:7]
	s_mov_b32 m0, s68
	ds_read_b128 v[162:165], v218 offset:49152
	ds_read_b128 v[166:169], v218 offset:50176
	ds_read_b128 v[170:173], v218 offset:51200
	ds_read_b128 v[174:177], v218 offset:52224
	ds_read_b128 v[178:181], v218 offset:53248
	ds_read_b128 v[220:223], v218 offset:54272
	ds_read_b128 v[224:227], v218 offset:55296
	ds_read_b128 v[228:231], v218 offset:56320
	global_load_lds_dwordx4 v[232:233], off
	s_add_i32 m0, s68, 0x2000
	s_add_u32 s66, s66, 0x8080
	v_lshl_add_u64 v[232:233], v[234:235], 0, s[6:7]
	s_addc_u32 s67, s67, 0
	s_add_i32 s68, s83, s31
	global_load_lds_dwordx4 v[232:233], off
	v_lshl_add_u64 v[232:233], s[66:67], 0, v[200:201]
	s_mov_b32 m0, s68
	s_nop 0
	global_load_lds_dwordx4 v[232:233], off
	v_lshl_add_u64 v[232:233], s[66:67], 0, v[204:205]
	s_add_i32 m0, s68, 0x2000
	s_nop 0
	global_load_lds_dwordx4 v[232:233], off
	v_lshl_add_u64 v[232:233], v[236:237], 0, s[6:7]
	s_mov_b32 m0, s4
	s_nop 0
	global_load_lds_dwordx4 v[232:233], off
	v_lshl_add_u64 v[232:233], v[238:239], 0, s[6:7]
	s_mov_b32 m0, s76
	s_nop 0
	global_load_lds_dwordx4 v[232:233], off
	s_waitcnt vmcnt(8)
	s_waitcnt lgkmcnt(0)
	s_barrier
	s_setprio 1
	s_waitcnt lgkmcnt(0)
	v_mfma_f32_16x16x32_bf16 v[60:63], v[76:79], v[162:165], v[60:63]
	v_mfma_f32_16x16x32_bf16 v[52:55], v[90:93], v[162:165], v[52:55]
	v_mfma_f32_16x16x32_bf16 v[44:47], v[76:79], v[170:173], v[44:47]
	v_mfma_f32_16x16x32_bf16 v[36:39], v[90:93], v[170:173], v[36:39]
	v_mfma_f32_16x16x32_bf16 v[28:31], v[76:79], v[178:181], v[28:31]
	v_mfma_f32_16x16x32_bf16 v[20:23], v[90:93], v[178:181], v[20:23]
	v_mfma_f32_16x16x32_bf16 v[12:15], v[76:79], v[224:227], v[12:15]
	v_mfma_f32_16x16x32_bf16 v[4:7], v[90:93], v[224:227], v[4:7]
	v_mfma_f32_16x16x32_bf16 v[60:63], v[82:85], v[166:169], v[60:63]
	v_mfma_f32_16x16x32_bf16 v[52:55], v[94:97], v[166:169], v[52:55]
	v_mfma_f32_16x16x32_bf16 v[44:47], v[82:85], v[174:177], v[44:47]
	v_mfma_f32_16x16x32_bf16 v[36:39], v[94:97], v[174:177], v[36:39]
	v_mfma_f32_16x16x32_bf16 v[28:31], v[82:85], v[220:223], v[28:31]
	v_mfma_f32_16x16x32_bf16 v[20:23], v[94:97], v[220:223], v[20:23]
	v_mfma_f32_16x16x32_bf16 v[12:15], v[82:85], v[228:231], v[12:15]
	v_mfma_f32_16x16x32_bf16 v[4:7], v[94:97], v[228:231], v[4:7]
	v_mfma_f32_16x16x32_bf16 v[56:59], v[98:101], v[162:165], v[56:59]
	v_mfma_f32_16x16x32_bf16 v[48:51], v[134:137], v[162:165], v[48:51]
	v_mfma_f32_16x16x32_bf16 v[40:43], v[98:101], v[170:173], v[40:43]
	v_mfma_f32_16x16x32_bf16 v[32:35], v[134:137], v[170:173], v[32:35]
	v_mfma_f32_16x16x32_bf16 v[24:27], v[98:101], v[178:181], v[24:27]
	v_mfma_f32_16x16x32_bf16 v[16:19], v[134:137], v[178:181], v[16:19]
	v_mfma_f32_16x16x32_bf16 v[8:11], v[98:101], v[224:227], v[8:11]
	v_mfma_f32_16x16x32_bf16 v[0:3], v[134:137], v[224:227], v[0:3]
	v_mfma_f32_16x16x32_bf16 v[56:59], v[114:117], v[166:169], v[56:59]
	v_mfma_f32_16x16x32_bf16 v[48:51], v[150:153], v[166:169], v[48:51]
	v_mfma_f32_16x16x32_bf16 v[40:43], v[114:117], v[174:177], v[40:43]
	v_mfma_f32_16x16x32_bf16 v[32:35], v[150:153], v[174:177], v[32:35]
	v_mfma_f32_16x16x32_bf16 v[24:27], v[114:117], v[220:223], v[24:27]
	v_mfma_f32_16x16x32_bf16 v[16:19], v[150:153], v[220:223], v[16:19]
	v_mfma_f32_16x16x32_bf16 v[8:11], v[114:117], v[228:231], v[8:11]
	v_mfma_f32_16x16x32_bf16 v[0:3], v[150:153], v[228:231], v[0:3]
	s_setprio 0
	s_barrier
	s_add_u32 s64, s64, 0x100
	s_addc_u32 s65, s65, 0
	s_add_u32 s59, s59, 0x100
	s_addc_u32 s80, s80, 0
	s_cmp_ge_i32 s81, s18
	s_mov_b32 s66, s81
	s_cbranch_scc0 .LBB0_320
	s_and_b64 vcc, exec, s[54:55]
	s_cbranch_vccz .LBB0_323

; #define PG8_STAGE(bufoff, gbase, voff) do { _Pragma("unroll") for (int _i = 0; _i < 2; ++_i) \
;         __builtin_amdgcn_global_load_lds((const unsigned*)((const char*)(gbase) + (voff)[_i]), (LAS unsigned*)(lds + (bufoff) + ldsw + _i * 8192), 16, 0, 0); } while (0)
; #define PG8_LDA(dst, b, h) do { _Pragma("unroll") for (int m = 0; m < 4; ++m) _Pragma("unroll") for (int k = 0; k < 2; ++k) dst[m][k] = *(const LAS bf16x8*)(lds + PG8_SA(b, h) + aoff + m * 2048 + k * 1024); } while (0)
; #define PG8_LDB(dst, b, h) do { _Pragma("unroll") for (int n = 0; n < 2; ++n) _Pragma("unroll") for (int k = 0; k < 2; ++k) dst[n][k] = *(const LAS bf16x8*)(lds + PG8_SB(b, h) + boff + n * 2048 + k * 1024); } while (0)
; #define PG8_MMA(ai, bj, At, Bt) do { __builtin_amdgcn_s_setprio(1); _Pragma("unroll") for (int m = 0; m < 4; ++m) _Pragma("unroll") for (int n = 0; n < 2; ++n) _Pragma("unroll") for (int k = 0; k < 2; ++k) \
;         acc[ai][bj][m][n] = MFMA16(Bt[n][k], At[m][k], acc[ai][bj][m][n]); __builtin_amdgcn_s_setprio(0); } while (0)
; #define PG8_WAIT_V(n) asm volatile("s_waitcnt vmcnt(" #n ")" ::: "memory")
; #define PG8_WAIT_L(n) asm volatile("s_waitcnt lgkmcnt(" #n ")" ::: "memory")
; #define PG8_BAR __builtin_amdgcn_s_barrier()
; #define PG8_SCHED __builtin_amdgcn_sched_barrier(0)
; template <class Epi>
; __device__ __forceinline__ void gemm_phase(LAS unsigned char* lds, const Gemm g, const StaticOrder& S, const Epi& E, int tid_) {
;     ...
;             const bool last = (t == nt - 2);
;             const char* a1 = cA + (size_t)(t + 1) * kstep;
;             const char* a2 = last ? nA : cA + (size_t)(t + 2) * kstep; const char* b2 = last ? nB : cB + (size_t)(t + 2) * kstep;
;             const char* a3 = a2 + kstep; const char* b3 = b2 + kstep;
;             PG8_LDB(B0, 0, 0); PG8_LDB(B1, 0, 1); PG8_SCHED; PG8_LDA(At, 0, 0); PG8_STAGE(PG8_SA(1, 1), a1 + hsA, voffA);
;             PG8_WAIT_V(8); PG8_WAIT_L(0); PG8_BAR; PG8_MMA(0, 0, At, B0); PG8_MMA(0, 1, At, B1); PG8_BAR; PG8_SCHED;
;             PG8_LDA(At, 0, 1); PG8_STAGE(PG8_SB(0, 0), b2, voffB); PG8_STAGE(PG8_SB(0, 1), b2 + hsB, voffB); PG8_STAGE(PG8_SA(0, 0), a2, voffA);
;             PG8_WAIT_V(8); PG8_WAIT_L(0); PG8_BAR; PG8_MMA(1, 0, At, B0); PG8_MMA(1, 1, At, B1); PG8_BAR; PG8_SCHED;
.LBB0_455:
	s_add_i32 s74, s40, 2
	s_add_u32 s41, s28, 0xfffc0080
	s_addc_u32 s60, s29, -1
	s_add_i32 s75, 0, 0x10000
	s_cmp_eq_u32 s68, s40
	s_cselect_b32 s61, s22, s60
	s_cselect_b32 s60, s23, s41
	s_cselect_b32 s41, s25, s73
	s_cselect_b32 s40, s51, s72
	s_add_i32 s78, 0, 0x14000
	v_add_u32_e32 v142, s75, v165
	v_add_u32_e32 v162, s78, v165
	ds_read_b128 v[130:133], v142
	s_waitcnt lgkmcnt(0)
	ds_read_b128 v[134:137], v142 offset:1024
	ds_read_b128 v[138:141], v142 offset:2048
	ds_read_b128 v[142:145], v142 offset:3072
	ds_read_b128 v[158:161], v162
	ds_read_b128 v[174:177], v162 offset:1024
	ds_read_b128 v[178:181], v162 offset:2048
	ds_read_b128 v[198:201], v162 offset:3072
	v_lshl_add_u64 v[162:163], s[28:29], 0, v[154:155]
	s_add_i32 m0, s62, 0xc000
	ds_read_b128 v[202:205], v173
	ds_read_b128 v[206:209], v173 offset:1024
	ds_read_b128 v[216:219], v173 offset:2048
	ds_read_b128 v[220:223], v173 offset:3072
	ds_read_b128 v[224:227], v173 offset:4096
	ds_read_b128 v[228:231], v173 offset:5120
	ds_read_b128 v[232:235], v173 offset:6144
	ds_read_b128 v[236:239], v173 offset:7168
	global_load_lds_dwordx4 v[162:163], off
	v_lshl_add_u64 v[162:163], s[28:29], 0, v[156:157]
	s_add_i32 m0, s62, 0xe000
	s_nop 0
	global_load_lds_dwordx4 v[162:163], off
	s_waitcnt vmcnt(8)
	s_waitcnt lgkmcnt(0)
	s_barrier
	s_setprio 1
	s_waitcnt lgkmcnt(0)
	v_mfma_f32_16x16x32_bf16 v[126:129], v[130:133], v[202:205], v[126:129]
	v_mfma_f32_16x16x32_bf16 v[122:125], v[138:141], v[202:205], v[122:125]
	v_mfma_f32_16x16x32_bf16 v[110:113], v[130:133], v[216:219], v[110:113]
	v_mfma_f32_16x16x32_bf16 v[106:109], v[138:141], v[216:219], v[106:109]
	v_mfma_f32_16x16x32_bf16 v[94:97], v[130:133], v[224:227], v[94:97]
	v_mfma_f32_16x16x32_bf16 v[90:93], v[138:141], v[224:227], v[90:93]
	v_mfma_f32_16x16x32_bf16 v[76:79], v[130:133], v[232:235], v[76:79]
	v_mfma_f32_16x16x32_bf16 v[72:75], v[138:141], v[232:235], v[72:75]
	v_mfma_f32_16x16x32_bf16 v[126:129], v[134:137], v[206:209], v[126:129]
	v_mfma_f32_16x16x32_bf16 v[122:125], v[142:145], v[206:209], v[122:125]
	v_mfma_f32_16x16x32_bf16 v[110:113], v[134:137], v[220:223], v[110:113]
	v_mfma_f32_16x16x32_bf16 v[106:109], v[142:145], v[220:223], v[106:109]
	v_mfma_f32_16x16x32_bf16 v[94:97], v[134:137], v[228:231], v[94:97]
	v_mfma_f32_16x16x32_bf16 v[90:93], v[142:145], v[228:231], v[90:93]
	v_mfma_f32_16x16x32_bf16 v[76:79], v[134:137], v[236:239], v[76:79]
	v_mfma_f32_16x16x32_bf16 v[72:75], v[142:145], v[236:239], v[72:75]
	v_mfma_f32_16x16x32_bf16 v[118:121], v[158:161], v[202:205], v[118:121]
	v_mfma_f32_16x16x32_bf16 v[114:117], v[178:181], v[202:205], v[114:117]
	v_mfma_f32_16x16x32_bf16 v[102:105], v[158:161], v[216:219], v[102:105]
	v_mfma_f32_16x16x32_bf16 v[98:101], v[178:181], v[216:219], v[98:101]
	v_mfma_f32_16x16x32_bf16 v[86:89], v[158:161], v[224:227], v[86:89]
	v_mfma_f32_16x16x32_bf16 v[82:85], v[178:181], v[224:227], v[82:85]
	v_mfma_f32_16x16x32_bf16 v[68:71], v[158:161], v[232:235], v[68:71]
	v_mfma_f32_16x16x32_bf16 v[64:67], v[178:181], v[232:235], v[64:67]
	v_mfma_f32_16x16x32_bf16 v[118:121], v[174:177], v[206:209], v[118:121]
	v_mfma_f32_16x16x32_bf16 v[114:117], v[198:201], v[206:209], v[114:117]
	v_mfma_f32_16x16x32_bf16 v[102:105], v[174:177], v[220:223], v[102:105]
	v_mfma_f32_16x16x32_bf16 v[98:101], v[198:201], v[220:223], v[98:101]
	v_mfma_f32_16x16x32_bf16 v[86:89], v[174:177], v[228:231], v[86:89]
	v_mfma_f32_16x16x32_bf16 v[82:85], v[198:201], v[228:231], v[82:85]
	v_mfma_f32_16x16x32_bf16 v[68:71], v[174:177], v[236:239], v[68:71]
	v_mfma_f32_16x16x32_bf16 v[64:67], v[198:201], v[236:239], v[64:67]
	s_setprio 0
	s_barrier
	s_add_i32 s75, s75, s31
	v_lshl_add_u64 v[162:163], s[40:41], 0, v[150:151]
	s_mov_b32 m0, s75
	ds_read_b128 v[202:205], v173 offset:16384
	ds_read_b128 v[206:209], v173 offset:17408
	ds_read_b128 v[216:219], v173 offset:18432
	ds_read_b128 v[220:223], v173 offset:19456
	ds_read_b128 v[224:227], v173 offset:20480
	ds_read_b128 v[228:231], v173 offset:21504
	ds_read_b128 v[232:235], v173 offset:22528
	ds_read_b128 v[236:239], v173 offset:23552
	global_load_lds_dwordx4 v[162:163], off
	s_add_i32 m0, s75, 0x2000
	s_add_u32 s76, s40, 0x40000
	v_lshl_add_u64 v[240:241], s[40:41], 0, v[146:147]
	s_addc_u32 s77, s41, 0
	s_add_i32 s75, s78, s31
	global_load_lds_dwordx4 v[240:241], off
	v_lshl_add_u64 v[242:243], s[76:77], 0, v[150:151]
	s_mov_b32 m0, s75
	v_lshl_add_u64 v[244:245], s[60:61], 0, v[148:149]
	global_load_lds_dwordx4 v[242:243], off
	v_lshl_add_u64 v[242:243], s[76:77], 0, v[146:147]
	s_add_i32 m0, s75, 0x2000
	s_nop 0
	global_load_lds_dwordx4 v[242:243], off
	v_lshl_add_u64 v[242:243], s[60:61], 0, v[152:153]
	s_mov_b32 m0, s62
	s_nop 0
	global_load_lds_dwordx4 v[242:243], off
	s_mov_b32 m0, s63
	s_nop 0
	global_load_lds_dwordx4 v[244:245], off
	s_waitcnt vmcnt(8)
	s_waitcnt lgkmcnt(0)
	s_barrier
; #define PG8_STAGE(bufoff, gbase, voff) do { _Pragma("unroll") for (int _i = 0; _i < 2; ++_i) \
;         __builtin_amdgcn_global_load_lds((const unsigned*)((const char*)(gbase) + (voff)[_i]), (LAS unsigned*)(lds + (bufoff) + ldsw + _i * 8192), 16, 0, 0); } while (0)
; #define PG8_LDA(dst, b, h) do { _Pragma("unroll") for (int m = 0; m < 4; ++m) _Pragma("unroll") for (int k = 0; k < 2; ++k) dst[m][k] = *(const LAS bf16x8*)(lds + PG8_SA(b, h) + aoff + m * 2048 + k * 1024); } while (0)
; #define PG8_LDB(dst, b, h) do { _Pragma("unroll") for (int n = 0; n < 2; ++n) _Pragma("unroll") for (int k = 0; k < 2; ++k) dst[n][k] = *(const LAS bf16x8*)(lds + PG8_SB(b, h) + boff + n * 2048 + k * 1024); } while (0)
; #define PG8_MMA(ai, bj, At, Bt) do { __builtin_amdgcn_s_setprio(1); _Pragma("unroll") for (int m = 0; m < 4; ++m) _Pragma("unroll") for (int n = 0; n < 2; ++n) _Pragma("unroll") for (int k = 0; k < 2; ++k) \
;         acc[ai][bj][m][n] = MFMA16(Bt[n][k], At[m][k], acc[ai][bj][m][n]); __builtin_amdgcn_s_setprio(0); } while (0)
; #define PG8_WAIT_V(n) asm volatile("s_waitcnt vmcnt(" #n ")" ::: "memory")
; #define PG8_WAIT_L(n) asm volatile("s_waitcnt lgkmcnt(" #n ")" ::: "memory")
; #define PG8_BAR __builtin_amdgcn_s_barrier()
; #define PG8_SCHED __builtin_amdgcn_sched_barrier(0)
; template <class Epi>
; __device__ __forceinline__ void gemm_phase(LAS unsigned char* lds, const Gemm g, const StaticOrder& S, const Epi& E, int tid_) {
;     ...
;             PG8_WAIT_V(8); PG8_WAIT_L(0); PG8_BAR; PG8_MMA(1, 0, At, B0); PG8_MMA(1, 1, At, B1); PG8_BAR; PG8_SCHED;
;             PG8_LDB(B0, 1, 0); PG8_LDB(B1, 1, 1); PG8_SCHED; PG8_LDA(At, 1, 0); PG8_STAGE(PG8_SA(0, 1), a2 + hsA, voffA);
;             PG8_WAIT_V(8); PG8_WAIT_L(0); PG8_BAR; PG8_MMA(0, 0, At, B0); PG8_MMA(0, 1, At, B1); PG8_BAR; PG8_SCHED;
	s_setprio 1
	s_waitcnt lgkmcnt(0)
	v_mfma_f32_16x16x32_bf16 v[60:63], v[130:133], v[202:205], v[60:63]
	v_mfma_f32_16x16x32_bf16 v[56:59], v[138:141], v[202:205], v[56:59]
	v_mfma_f32_16x16x32_bf16 v[44:47], v[130:133], v[216:219], v[44:47]
	v_mfma_f32_16x16x32_bf16 v[40:43], v[138:141], v[216:219], v[40:43]
	v_mfma_f32_16x16x32_bf16 v[28:31], v[130:133], v[224:227], v[28:31]
	v_mfma_f32_16x16x32_bf16 v[24:27], v[138:141], v[224:227], v[24:27]
	v_mfma_f32_16x16x32_bf16 v[12:15], v[130:133], v[232:235], v[12:15]
	v_mfma_f32_16x16x32_bf16 v[8:11], v[138:141], v[232:235], v[8:11]
	v_mfma_f32_16x16x32_bf16 v[60:63], v[134:137], v[206:209], v[60:63]
	v_mfma_f32_16x16x32_bf16 v[56:59], v[142:145], v[206:209], v[56:59]
	v_mfma_f32_16x16x32_bf16 v[44:47], v[134:137], v[220:223], v[44:47]
	v_mfma_f32_16x16x32_bf16 v[40:43], v[142:145], v[220:223], v[40:43]
	v_mfma_f32_16x16x32_bf16 v[28:31], v[134:137], v[228:231], v[28:31]
	v_mfma_f32_16x16x32_bf16 v[24:27], v[142:145], v[228:231], v[24:27]
	v_mfma_f32_16x16x32_bf16 v[12:15], v[134:137], v[236:239], v[12:15]
	v_mfma_f32_16x16x32_bf16 v[8:11], v[142:145], v[236:239], v[8:11]
	v_mfma_f32_16x16x32_bf16 v[52:55], v[158:161], v[202:205], v[52:55]
	v_mfma_f32_16x16x32_bf16 v[48:51], v[178:181], v[202:205], v[48:51]
	v_mfma_f32_16x16x32_bf16 v[36:39], v[158:161], v[216:219], v[36:39]
	v_mfma_f32_16x16x32_bf16 v[32:35], v[178:181], v[216:219], v[32:35]
	v_mfma_f32_16x16x32_bf16 v[20:23], v[158:161], v[224:227], v[20:23]
	v_mfma_f32_16x16x32_bf16 v[16:19], v[178:181], v[224:227], v[16:19]
	v_mfma_f32_16x16x32_bf16 v[4:7], v[158:161], v[232:235], v[4:7]
	v_mfma_f32_16x16x32_bf16 v[0:3], v[178:181], v[232:235], v[0:3]
	v_mfma_f32_16x16x32_bf16 v[52:55], v[174:177], v[206:209], v[52:55]
	v_mfma_f32_16x16x32_bf16 v[48:51], v[198:201], v[206:209], v[48:51]
	v_mfma_f32_16x16x32_bf16 v[36:39], v[174:177], v[220:223], v[36:39]
	v_mfma_f32_16x16x32_bf16 v[32:35], v[198:201], v[220:223], v[32:35]
	v_mfma_f32_16x16x32_bf16 v[20:23], v[174:177], v[228:231], v[20:23]
	v_mfma_f32_16x16x32_bf16 v[16:19], v[198:201], v[228:231], v[16:19]
	v_mfma_f32_16x16x32_bf16 v[4:7], v[174:177], v[236:239], v[4:7]
	v_mfma_f32_16x16x32_bf16 v[0:3], v[198:201], v[236:239], v[0:3]
	s_setprio 0
	s_barrier
	s_add_i32 s75, 0, 0x18000
	s_add_i32 s76, 0, 0x1c000
	v_add_u32_e32 v142, s75, v165
	v_add_u32_e32 v198, s76, v165
	ds_read_b128 v[130:133], v142
	ds_read_b128 v[134:137], v142 offset:1024
	ds_read_b128 v[138:141], v142 offset:2048
	ds_read_b128 v[142:145], v142 offset:3072
	ds_read_b128 v[158:161], v198
	ds_read_b128 v[174:177], v198 offset:1024
	ds_read_b128 v[178:181], v198 offset:2048
	ds_read_b128 v[198:201], v198 offset:3072
	s_add_u32 s60, s60, 0x40000
	s_addc_u32 s61, s61, 0
	s_mov_b32 m0, s64
	v_lshl_add_u64 v[246:247], s[60:61], 0, v[152:153]
	ds_read_b128 v[202:205], v173 offset:32768
	ds_read_b128 v[206:209], v173 offset:33792
	ds_read_b128 v[216:219], v173 offset:34816
	ds_read_b128 v[220:223], v173 offset:35840
	ds_read_b128 v[224:227], v173 offset:36864
	ds_read_b128 v[228:231], v173 offset:37888
	ds_read_b128 v[232:235], v173 offset:38912
	ds_read_b128 v[236:239], v173 offset:39936
	global_load_lds_dwordx4 v[246:247], off
	v_lshl_add_u64 v[246:247], s[60:61], 0, v[148:149]
	s_mov_b32 m0, s65
	s_nop 0
	global_load_lds_dwordx4 v[246:247], off
	s_waitcnt vmcnt(8)
	s_waitcnt lgkmcnt(0)
	s_barrier
	s_setprio 1
	s_waitcnt lgkmcnt(0)
	v_mfma_f32_16x16x32_bf16 v[126:129], v[130:133], v[202:205], v[126:129]
	v_mfma_f32_16x16x32_bf16 v[122:125], v[138:141], v[202:205], v[122:125]
	v_mfma_f32_16x16x32_bf16 v[110:113], v[130:133], v[216:219], v[110:113]
	v_mfma_f32_16x16x32_bf16 v[106:109], v[138:141], v[216:219], v[106:109]
	v_mfma_f32_16x16x32_bf16 v[94:97], v[130:133], v[224:227], v[94:97]
	v_mfma_f32_16x16x32_bf16 v[90:93], v[138:141], v[224:227], v[90:93]
	v_mfma_f32_16x16x32_bf16 v[76:79], v[130:133], v[232:235], v[76:79]
	v_mfma_f32_16x16x32_bf16 v[72:75], v[138:141], v[232:235], v[72:75]
	v_mfma_f32_16x16x32_bf16 v[126:129], v[134:137], v[206:209], v[126:129]
	v_mfma_f32_16x16x32_bf16 v[122:125], v[142:145], v[206:209], v[122:125]
	v_mfma_f32_16x16x32_bf16 v[110:113], v[134:137], v[220:223], v[110:113]
	v_mfma_f32_16x16x32_bf16 v[106:109], v[142:145], v[220:223], v[106:109]
	v_mfma_f32_16x16x32_bf16 v[94:97], v[134:137], v[228:231], v[94:97]
	v_mfma_f32_16x16x32_bf16 v[90:93], v[142:145], v[228:231], v[90:93]
	v_mfma_f32_16x16x32_bf16 v[76:79], v[134:137], v[236:239], v[76:79]
	v_mfma_f32_16x16x32_bf16 v[72:75], v[142:145], v[236:239], v[72:75]
	v_mfma_f32_16x16x32_bf16 v[118:121], v[158:161], v[202:205], v[118:121]
	v_mfma_f32_16x16x32_bf16 v[114:117], v[178:181], v[202:205], v[114:117]
	v_mfma_f32_16x16x32_bf16 v[102:105], v[158:161], v[216:219], v[102:105]
	v_mfma_f32_16x16x32_bf16 v[98:101], v[178:181], v[216:219], v[98:101]
	v_mfma_f32_16x16x32_bf16 v[86:89], v[158:161], v[224:227], v[86:89]
	v_mfma_f32_16x16x32_bf16 v[82:85], v[178:181], v[224:227], v[82:85]
	v_mfma_f32_16x16x32_bf16 v[68:71], v[158:161], v[232:235], v[68:71]
	v_mfma_f32_16x16x32_bf16 v[64:67], v[178:181], v[232:235], v[64:67]
	v_mfma_f32_16x16x32_bf16 v[118:121], v[174:177], v[206:209], v[118:121]
	v_mfma_f32_16x16x32_bf16 v[114:117], v[198:201], v[206:209], v[114:117]
	v_mfma_f32_16x16x32_bf16 v[102:105], v[174:177], v[220:223], v[102:105]
	v_mfma_f32_16x16x32_bf16 v[98:101], v[198:201], v[220:223], v[98:101]
	v_mfma_f32_16x16x32_bf16 v[86:89], v[174:177], v[228:231], v[86:89]
	v_mfma_f32_16x16x32_bf16 v[82:85], v[198:201], v[228:231], v[82:85]
	v_mfma_f32_16x16x32_bf16 v[68:71], v[174:177], v[236:239], v[68:71]
	v_mfma_f32_16x16x32_bf16 v[64:67], v[198:201], v[236:239], v[64:67]
	s_setprio 0
	s_barrier
; #define PG8_STAGE(bufoff, gbase, voff) do { _Pragma("unroll") for (int _i = 0; _i < 2; ++_i) \
;         __builtin_amdgcn_global_load_lds((const unsigned*)((const char*)(gbase) + (voff)[_i]), (LAS unsigned*)(lds + (bufoff) + ldsw + _i * 8192), 16, 0, 0); } while (0)
; #define PG8_LDA(dst, b, h) do { _Pragma("unroll") for (int m = 0; m < 4; ++m) _Pragma("unroll") for (int k = 0; k < 2; ++k) dst[m][k] = *(const LAS bf16x8*)(lds + PG8_SA(b, h) + aoff + m * 2048 + k * 1024); } while (0)
; #define PG8_MMA(ai, bj, At, Bt) do { __builtin_amdgcn_s_setprio(1); _Pragma("unroll") for (int m = 0; m < 4; ++m) _Pragma("unroll") for (int n = 0; n < 2; ++n) _Pragma("unroll") for (int k = 0; k < 2; ++k) \
;         acc[ai][bj][m][n] = MFMA16(Bt[n][k], At[m][k], acc[ai][bj][m][n]); __builtin_amdgcn_s_setprio(0); } while (0)
; #define PG8_WAIT_V(n) asm volatile("s_waitcnt vmcnt(" #n ")" ::: "memory")
; #define PG8_WAIT_L(n) asm volatile("s_waitcnt lgkmcnt(" #n ")" ::: "memory")
; #define PG8_BAR __builtin_amdgcn_s_barrier()
; #define PG8_SCHED __builtin_amdgcn_sched_barrier(0)
; template <class Epi>
; __device__ __forceinline__ void gemm_phase(LAS unsigned char* lds, const Gemm g, const StaticOrder& S, const Epi& E, int tid_) {
;     ...
;         for (int t = 0; t < nt; t += 2) {
;     ...
;             PG8_LDA(At, 1, 1); PG8_STAGE(PG8_SB(1, 0), b3, voffB); PG8_STAGE(PG8_SB(1, 1), b3 + hsB, voffB); PG8_STAGE(PG8_SA(1, 0), a3, voffA);
;             PG8_WAIT_V(8); PG8_WAIT_L(0); PG8_BAR; PG8_MMA(1, 0, At, B0); PG8_MMA(1, 1, At, B1); PG8_BAR; PG8_SCHED;
;         }
	s_add_i32 s60, s75, s31
	v_lshl_add_u64 v[162:163], v[162:163], 0, s[6:7]
	s_mov_b32 m0, s60
	ds_read_b128 v[202:205], v173 offset:49152
	ds_read_b128 v[206:209], v173 offset:50176
	ds_read_b128 v[216:219], v173 offset:51200
	ds_read_b128 v[220:223], v173 offset:52224
	ds_read_b128 v[224:227], v173 offset:53248
	ds_read_b128 v[228:231], v173 offset:54272
	ds_read_b128 v[232:235], v173 offset:55296
	ds_read_b128 v[236:239], v173 offset:56320
	global_load_lds_dwordx4 v[162:163], off
	s_add_i32 m0, s60, 0x2000
	s_add_u32 s40, s40, 0x40080
	v_lshl_add_u64 v[162:163], v[240:241], 0, s[6:7]
	s_addc_u32 s41, s41, 0
	s_add_i32 s60, s76, s31
	global_load_lds_dwordx4 v[162:163], off
	v_lshl_add_u64 v[162:163], s[40:41], 0, v[150:151]
	s_mov_b32 m0, s60
	s_nop 0
	global_load_lds_dwordx4 v[162:163], off
	v_lshl_add_u64 v[162:163], s[40:41], 0, v[146:147]
	s_add_i32 m0, s60, 0x2000
	s_nop 0
	global_load_lds_dwordx4 v[162:163], off
	v_lshl_add_u64 v[162:163], v[242:243], 0, s[6:7]
	s_mov_b32 m0, s4
	s_nop 0
	global_load_lds_dwordx4 v[162:163], off
	v_lshl_add_u64 v[162:163], v[244:245], 0, s[6:7]
	s_mov_b32 m0, s66
	s_nop 0
	global_load_lds_dwordx4 v[162:163], off
	s_waitcnt vmcnt(8)
	s_waitcnt lgkmcnt(0)
	s_barrier
	s_setprio 1
	s_waitcnt lgkmcnt(0)
	v_mfma_f32_16x16x32_bf16 v[60:63], v[130:133], v[202:205], v[60:63]
	v_mfma_f32_16x16x32_bf16 v[56:59], v[138:141], v[202:205], v[56:59]
	v_mfma_f32_16x16x32_bf16 v[44:47], v[130:133], v[216:219], v[44:47]
	v_mfma_f32_16x16x32_bf16 v[40:43], v[138:141], v[216:219], v[40:43]
	v_mfma_f32_16x16x32_bf16 v[28:31], v[130:133], v[224:227], v[28:31]
	v_mfma_f32_16x16x32_bf16 v[24:27], v[138:141], v[224:227], v[24:27]
	v_mfma_f32_16x16x32_bf16 v[12:15], v[130:133], v[232:235], v[12:15]
	v_mfma_f32_16x16x32_bf16 v[8:11], v[138:141], v[232:235], v[8:11]
	v_mfma_f32_16x16x32_bf16 v[60:63], v[134:137], v[206:209], v[60:63]
	v_mfma_f32_16x16x32_bf16 v[56:59], v[142:145], v[206:209], v[56:59]
	v_mfma_f32_16x16x32_bf16 v[44:47], v[134:137], v[220:223], v[44:47]
	v_mfma_f32_16x16x32_bf16 v[40:43], v[142:145], v[220:223], v[40:43]
	v_mfma_f32_16x16x32_bf16 v[28:31], v[134:137], v[228:231], v[28:31]
	v_mfma_f32_16x16x32_bf16 v[24:27], v[142:145], v[228:231], v[24:27]
	v_mfma_f32_16x16x32_bf16 v[12:15], v[134:137], v[236:239], v[12:15]
	v_mfma_f32_16x16x32_bf16 v[8:11], v[142:145], v[236:239], v[8:11]
	v_mfma_f32_16x16x32_bf16 v[52:55], v[158:161], v[202:205], v[52:55]
	v_mfma_f32_16x16x32_bf16 v[48:51], v[178:181], v[202:205], v[48:51]
	v_mfma_f32_16x16x32_bf16 v[36:39], v[158:161], v[216:219], v[36:39]
	v_mfma_f32_16x16x32_bf16 v[32:35], v[178:181], v[216:219], v[32:35]
	v_mfma_f32_16x16x32_bf16 v[20:23], v[158:161], v[224:227], v[20:23]
	v_mfma_f32_16x16x32_bf16 v[16:19], v[178:181], v[224:227], v[16:19]
	v_mfma_f32_16x16x32_bf16 v[4:7], v[158:161], v[232:235], v[4:7]
	v_mfma_f32_16x16x32_bf16 v[0:3], v[178:181], v[232:235], v[0:3]
	v_mfma_f32_16x16x32_bf16 v[52:55], v[174:177], v[206:209], v[52:55]
	v_mfma_f32_16x16x32_bf16 v[48:51], v[198:201], v[206:209], v[48:51]
	v_mfma_f32_16x16x32_bf16 v[36:39], v[174:177], v[220:223], v[36:39]
	v_mfma_f32_16x16x32_bf16 v[32:35], v[198:201], v[220:223], v[32:35]
	v_mfma_f32_16x16x32_bf16 v[20:23], v[174:177], v[228:231], v[20:23]
	v_mfma_f32_16x16x32_bf16 v[16:19], v[198:201], v[228:231], v[16:19]
	v_mfma_f32_16x16x32_bf16 v[4:7], v[174:177], v[236:239], v[4:7]
	v_mfma_f32_16x16x32_bf16 v[0:3], v[198:201], v[236:239], v[0:3]
	s_setprio 0
	s_barrier
	s_add_u32 s28, s28, 0x100
	s_addc_u32 s29, s29, 0
	s_add_u32 s72, s72, 0x100
	s_addc_u32 s73, s73, 0
	s_cmp_ge_i32 s74, s30
	s_mov_b32 s40, s74
	s_cbranch_scc0 .LBB0_455
	s_and_b64 vcc, exec, s[48:49]
	s_cbranch_vccz .LBB0_458

; #define PG8_STAGE(bufoff, gbase, voff) do { _Pragma("unroll") for (int _i = 0; _i < 2; ++_i) \
;         __builtin_amdgcn_global_load_lds((const unsigned*)((const char*)(gbase) + (voff)[_i]), (LAS unsigned*)(lds + (bufoff) + ldsw + _i * 8192), 16, 0, 0); } while (0)
; #define PG8_LDA(dst, b, h) do { _Pragma("unroll") for (int m = 0; m < 4; ++m) _Pragma("unroll") for (int k = 0; k < 2; ++k) dst[m][k] = *(const LAS bf16x8*)(lds + PG8_SA(b, h) + aoff + m * 2048 + k * 1024); } while (0)
; #define PG8_LDB(dst, b, h) do { _Pragma("unroll") for (int n = 0; n < 2; ++n) _Pragma("unroll") for (int k = 0; k < 2; ++k) dst[n][k] = *(const LAS bf16x8*)(lds + PG8_SB(b, h) + boff + n * 2048 + k * 1024); } while (0)
; #define PG8_MMA(ai, bj, At, Bt) do { __builtin_amdgcn_s_setprio(1); _Pragma("unroll") for (int m = 0; m < 4; ++m) _Pragma("unroll") for (int n = 0; n < 2; ++n) _Pragma("unroll") for (int k = 0; k < 2; ++k) \
;         acc[ai][bj][m][n] = MFMA16(Bt[n][k], At[m][k], acc[ai][bj][m][n]); __builtin_amdgcn_s_setprio(0); } while (0)
; #define PG8_WAIT_V(n) asm volatile("s_waitcnt vmcnt(" #n ")" ::: "memory")
; #define PG8_WAIT_L(n) asm volatile("s_waitcnt lgkmcnt(" #n ")" ::: "memory")
; #define PG8_BAR __builtin_amdgcn_s_barrier()
; #define PG8_SCHED __builtin_amdgcn_sched_barrier(0)
; template <class Epi>
; __device__ __forceinline__ void gemm_phase(LAS unsigned char* lds, const Gemm g, const StaticOrder& S, const Epi& E, int tid_) {
;     ...
;             const bool last = (t == nt - 2);
;             const char* a1 = cA + (size_t)(t + 1) * kstep;
;             const char* a2 = last ? nA : cA + (size_t)(t + 2) * kstep; const char* b2 = last ? nB : cB + (size_t)(t + 2) * kstep;
;             const char* a3 = a2 + kstep; const char* b3 = b2 + kstep;
;             PG8_LDB(B0, 0, 0); PG8_LDB(B1, 0, 1); PG8_SCHED; PG8_LDA(At, 0, 0); PG8_STAGE(PG8_SA(1, 1), a1 + hsA, voffA);
;             PG8_WAIT_V(8); PG8_WAIT_L(0); PG8_BAR; PG8_MMA(0, 0, At, B0); PG8_MMA(0, 1, At, B1); PG8_BAR; PG8_SCHED;
;             PG8_LDA(At, 0, 1); PG8_STAGE(PG8_SB(0, 0), b2, voffB); PG8_STAGE(PG8_SB(0, 1), b2 + hsB, voffB); PG8_STAGE(PG8_SA(0, 0), a2, voffA);
;             PG8_WAIT_V(8); PG8_WAIT_L(0); PG8_BAR; PG8_MMA(1, 0, At, B0); PG8_MMA(1, 1, At, B1); PG8_BAR; PG8_SCHED;
.LBB0_683:
	s_add_i32 s69, s54, 2
	s_add_u32 s70, s28, 0x80
	s_addc_u32 s55, s29, 0
	s_add_i32 s72, 0, 0x10000
	s_cmp_eq_u32 s63, s54
	s_cselect_b32 s55, s41, s55
	s_cselect_b32 s54, s40, s70
	s_cselect_b32 s71, s53, s23
	s_cselect_b32 s70, s52, s22
	s_add_i32 s73, 0, 0x14000
	v_add_u32_e32 v142, s72, v166
	v_add_u32_e32 v169, s73, v166
	ds_read_b128 v[130:133], v142
	ds_read_b128 v[134:137], v142 offset:1024
	ds_read_b128 v[138:141], v142 offset:2048
	ds_read_b128 v[142:145], v142 offset:3072
	ds_read_b128 v[146:149], v169
	ds_read_b128 v[150:153], v169 offset:1024
	ds_read_b128 v[170:173], v169 offset:2048
	ds_read_b128 v[174:177], v169 offset:3072
	v_lshl_add_u64 v[232:233], s[28:29], 0, v[162:163]
	s_add_i32 m0, s56, 0xc000
	ds_read_b128 v[178:181], v168
	ds_read_b128 v[198:201], v168 offset:1024
	ds_read_b128 v[202:205], v168 offset:2048
	ds_read_b128 v[206:209], v168 offset:3072
	ds_read_b128 v[216:219], v168 offset:4096
	ds_read_b128 v[220:223], v168 offset:5120
	ds_read_b128 v[224:227], v168 offset:6144
	ds_read_b128 v[228:231], v168 offset:7168
	global_load_lds_dwordx4 v[232:233], off
	v_lshl_add_u64 v[232:233], s[28:29], 0, v[164:165]
	s_add_i32 m0, s56, 0xe000
	s_nop 0
	global_load_lds_dwordx4 v[232:233], off
	s_waitcnt vmcnt(8)
	s_waitcnt lgkmcnt(0)
	s_barrier
	s_setprio 1
	s_waitcnt lgkmcnt(0)
	v_mfma_f32_16x16x32_bf16 v[126:129], v[130:133], v[178:181], v[126:129]
	v_mfma_f32_16x16x32_bf16 v[122:125], v[138:141], v[178:181], v[122:125]
	v_mfma_f32_16x16x32_bf16 v[110:113], v[130:133], v[202:205], v[110:113]
	v_mfma_f32_16x16x32_bf16 v[106:109], v[138:141], v[202:205], v[106:109]
	v_mfma_f32_16x16x32_bf16 v[94:97], v[130:133], v[216:219], v[94:97]
	v_mfma_f32_16x16x32_bf16 v[90:93], v[138:141], v[216:219], v[90:93]
	v_mfma_f32_16x16x32_bf16 v[76:79], v[130:133], v[224:227], v[76:79]
	v_mfma_f32_16x16x32_bf16 v[72:75], v[138:141], v[224:227], v[72:75]
	v_mfma_f32_16x16x32_bf16 v[126:129], v[134:137], v[198:201], v[126:129]
	v_mfma_f32_16x16x32_bf16 v[122:125], v[142:145], v[198:201], v[122:125]
	v_mfma_f32_16x16x32_bf16 v[110:113], v[134:137], v[206:209], v[110:113]
	v_mfma_f32_16x16x32_bf16 v[106:109], v[142:145], v[206:209], v[106:109]
	v_mfma_f32_16x16x32_bf16 v[94:97], v[134:137], v[220:223], v[94:97]
	v_mfma_f32_16x16x32_bf16 v[90:93], v[142:145], v[220:223], v[90:93]
	v_mfma_f32_16x16x32_bf16 v[76:79], v[134:137], v[228:231], v[76:79]
	v_mfma_f32_16x16x32_bf16 v[72:75], v[142:145], v[228:231], v[72:75]
	v_mfma_f32_16x16x32_bf16 v[118:121], v[146:149], v[178:181], v[118:121]
	v_mfma_f32_16x16x32_bf16 v[114:117], v[170:173], v[178:181], v[114:117]
	v_mfma_f32_16x16x32_bf16 v[102:105], v[146:149], v[202:205], v[102:105]
	v_mfma_f32_16x16x32_bf16 v[98:101], v[170:173], v[202:205], v[98:101]
	v_mfma_f32_16x16x32_bf16 v[86:89], v[146:149], v[216:219], v[86:89]
	v_mfma_f32_16x16x32_bf16 v[82:85], v[170:173], v[216:219], v[82:85]
	v_mfma_f32_16x16x32_bf16 v[68:71], v[146:149], v[224:227], v[68:71]
	v_mfma_f32_16x16x32_bf16 v[64:67], v[170:173], v[224:227], v[64:67]
	v_mfma_f32_16x16x32_bf16 v[118:121], v[150:153], v[198:201], v[118:121]
	v_mfma_f32_16x16x32_bf16 v[114:117], v[174:177], v[198:201], v[114:117]
	v_mfma_f32_16x16x32_bf16 v[102:105], v[150:153], v[206:209], v[102:105]
	v_mfma_f32_16x16x32_bf16 v[98:101], v[174:177], v[206:209], v[98:101]
	v_mfma_f32_16x16x32_bf16 v[86:89], v[150:153], v[220:223], v[86:89]
	v_mfma_f32_16x16x32_bf16 v[82:85], v[174:177], v[220:223], v[82:85]
	v_mfma_f32_16x16x32_bf16 v[68:71], v[150:153], v[228:231], v[68:71]
	v_mfma_f32_16x16x32_bf16 v[64:67], v[174:177], v[228:231], v[64:67]
	s_setprio 0
	s_barrier
	s_add_i32 s72, s72, s31
	v_lshl_add_u64 v[232:233], s[70:71], 0, v[156:157]
	s_mov_b32 m0, s72
	ds_read_b128 v[178:181], v168 offset:16384
	ds_read_b128 v[198:201], v168 offset:17408
	ds_read_b128 v[202:205], v168 offset:18432
	ds_read_b128 v[206:209], v168 offset:19456
	ds_read_b128 v[216:219], v168 offset:20480
	ds_read_b128 v[220:223], v168 offset:21504
	ds_read_b128 v[224:227], v168 offset:22528
	ds_read_b128 v[228:231], v168 offset:23552
	global_load_lds_dwordx4 v[232:233], off
	s_add_i32 m0, s72, 0x2000
	v_lshl_add_u64 v[234:235], s[70:71], 0, v[160:161]
	s_add_u32 s70, s70, s4
	s_addc_u32 s71, s71, 0
	s_add_i32 s72, s73, s31
	global_load_lds_dwordx4 v[234:235], off
	v_lshl_add_u64 v[236:237], s[70:71], 0, v[156:157]
	s_mov_b32 m0, s72
	v_lshl_add_u64 v[238:239], s[70:71], 0, v[160:161]
	global_load_lds_dwordx4 v[236:237], off
	s_add_i32 m0, s72, 0x2000
	v_lshl_add_u64 v[240:241], s[54:55], 0, v[154:155]
	global_load_lds_dwordx4 v[238:239], off
	s_mov_b32 m0, s56
	v_lshl_add_u64 v[242:243], s[54:55], 0, v[158:159]
	global_load_lds_dwordx4 v[240:241], off
	s_mov_b32 m0, s57
	s_nop 0
	global_load_lds_dwordx4 v[242:243], off
	s_waitcnt vmcnt(8)
	s_waitcnt lgkmcnt(0)
	s_barrier
; #define PG8_STAGE(bufoff, gbase, voff) do { _Pragma("unroll") for (int _i = 0; _i < 2; ++_i) \
;         __builtin_amdgcn_global_load_lds((const unsigned*)((const char*)(gbase) + (voff)[_i]), (LAS unsigned*)(lds + (bufoff) + ldsw + _i * 8192), 16, 0, 0); } while (0)
; #define PG8_LDA(dst, b, h) do { _Pragma("unroll") for (int m = 0; m < 4; ++m) _Pragma("unroll") for (int k = 0; k < 2; ++k) dst[m][k] = *(const LAS bf16x8*)(lds + PG8_SA(b, h) + aoff + m * 2048 + k * 1024); } while (0)
; #define PG8_LDB(dst, b, h) do { _Pragma("unroll") for (int n = 0; n < 2; ++n) _Pragma("unroll") for (int k = 0; k < 2; ++k) dst[n][k] = *(const LAS bf16x8*)(lds + PG8_SB(b, h) + boff + n * 2048 + k * 1024); } while (0)
; #define PG8_MMA(ai, bj, At, Bt) do { __builtin_amdgcn_s_setprio(1); _Pragma("unroll") for (int m = 0; m < 4; ++m) _Pragma("unroll") for (int n = 0; n < 2; ++n) _Pragma("unroll") for (int k = 0; k < 2; ++k) \
;         acc[ai][bj][m][n] = MFMA16(Bt[n][k], At[m][k], acc[ai][bj][m][n]); __builtin_amdgcn_s_setprio(0); } while (0)
; #define PG8_WAIT_V(n) asm volatile("s_waitcnt vmcnt(" #n ")" ::: "memory")
; #define PG8_WAIT_L(n) asm volatile("s_waitcnt lgkmcnt(" #n ")" ::: "memory")
; #define PG8_BAR __builtin_amdgcn_s_barrier()
; #define PG8_SCHED __builtin_amdgcn_sched_barrier(0)
; template <class Epi>
; __device__ __forceinline__ void gemm_phase(LAS unsigned char* lds, const Gemm g, const StaticOrder& S, const Epi& E, int tid_) {
;     ...
;             PG8_WAIT_V(8); PG8_WAIT_L(0); PG8_BAR; PG8_MMA(1, 0, At, B0); PG8_MMA(1, 1, At, B1); PG8_BAR; PG8_SCHED;
;             PG8_LDB(B0, 1, 0); PG8_LDB(B1, 1, 1); PG8_SCHED; PG8_LDA(At, 1, 0); PG8_STAGE(PG8_SA(0, 1), a2 + hsA, voffA);
;             PG8_WAIT_V(8); PG8_WAIT_L(0); PG8_BAR; PG8_MMA(0, 0, At, B0); PG8_MMA(0, 1, At, B1); PG8_BAR; PG8_SCHED;
	s_setprio 1
	s_waitcnt lgkmcnt(0)
	v_mfma_f32_16x16x32_bf16 v[60:63], v[130:133], v[178:181], v[60:63]
	v_mfma_f32_16x16x32_bf16 v[56:59], v[138:141], v[178:181], v[56:59]
	v_mfma_f32_16x16x32_bf16 v[44:47], v[130:133], v[202:205], v[44:47]
	v_mfma_f32_16x16x32_bf16 v[40:43], v[138:141], v[202:205], v[40:43]
	v_mfma_f32_16x16x32_bf16 v[28:31], v[130:133], v[216:219], v[28:31]
	v_mfma_f32_16x16x32_bf16 v[24:27], v[138:141], v[216:219], v[24:27]
	v_mfma_f32_16x16x32_bf16 v[12:15], v[130:133], v[224:227], v[12:15]
	v_mfma_f32_16x16x32_bf16 v[8:11], v[138:141], v[224:227], v[8:11]
	v_mfma_f32_16x16x32_bf16 v[60:63], v[134:137], v[198:201], v[60:63]
	v_mfma_f32_16x16x32_bf16 v[56:59], v[142:145], v[198:201], v[56:59]
	v_mfma_f32_16x16x32_bf16 v[44:47], v[134:137], v[206:209], v[44:47]
	v_mfma_f32_16x16x32_bf16 v[40:43], v[142:145], v[206:209], v[40:43]
	v_mfma_f32_16x16x32_bf16 v[28:31], v[134:137], v[220:223], v[28:31]
	v_mfma_f32_16x16x32_bf16 v[24:27], v[142:145], v[220:223], v[24:27]
	v_mfma_f32_16x16x32_bf16 v[12:15], v[134:137], v[228:231], v[12:15]
	v_mfma_f32_16x16x32_bf16 v[8:11], v[142:145], v[228:231], v[8:11]
	v_mfma_f32_16x16x32_bf16 v[52:55], v[146:149], v[178:181], v[52:55]
	v_mfma_f32_16x16x32_bf16 v[48:51], v[170:173], v[178:181], v[48:51]
	v_mfma_f32_16x16x32_bf16 v[36:39], v[146:149], v[202:205], v[36:39]
	v_mfma_f32_16x16x32_bf16 v[32:35], v[170:173], v[202:205], v[32:35]
	v_mfma_f32_16x16x32_bf16 v[20:23], v[146:149], v[216:219], v[20:23]
	v_mfma_f32_16x16x32_bf16 v[16:19], v[170:173], v[216:219], v[16:19]
	v_mfma_f32_16x16x32_bf16 v[4:7], v[146:149], v[224:227], v[4:7]
	v_mfma_f32_16x16x32_bf16 v[0:3], v[170:173], v[224:227], v[0:3]
	v_mfma_f32_16x16x32_bf16 v[52:55], v[150:153], v[198:201], v[52:55]
	v_mfma_f32_16x16x32_bf16 v[48:51], v[174:177], v[198:201], v[48:51]
	v_mfma_f32_16x16x32_bf16 v[36:39], v[150:153], v[206:209], v[36:39]
	v_mfma_f32_16x16x32_bf16 v[32:35], v[174:177], v[206:209], v[32:35]
	v_mfma_f32_16x16x32_bf16 v[20:23], v[150:153], v[220:223], v[20:23]
	v_mfma_f32_16x16x32_bf16 v[16:19], v[174:177], v[220:223], v[16:19]
	v_mfma_f32_16x16x32_bf16 v[4:7], v[150:153], v[228:231], v[4:7]
	v_mfma_f32_16x16x32_bf16 v[0:3], v[174:177], v[228:231], v[0:3]
	s_setprio 0
	s_barrier
	s_add_i32 s70, 0, 0x18000
	s_add_i32 s71, 0, 0x1c000
	v_add_u32_e32 v142, s70, v166
	v_add_u32_e32 v169, s71, v166
	ds_read_b128 v[130:133], v142
	ds_read_b128 v[134:137], v142 offset:1024
	ds_read_b128 v[138:141], v142 offset:2048
	ds_read_b128 v[142:145], v142 offset:3072
	ds_read_b128 v[146:149], v169
	ds_read_b128 v[150:153], v169 offset:1024
	ds_read_b128 v[170:173], v169 offset:2048
	ds_read_b128 v[174:177], v169 offset:3072
	s_add_u32 s54, s54, s4
	s_addc_u32 s55, s55, 0
	s_mov_b32 m0, s58
	v_lshl_add_u64 v[244:245], s[54:55], 0, v[154:155]
	ds_read_b128 v[178:181], v168 offset:32768
	ds_read_b128 v[198:201], v168 offset:33792
	ds_read_b128 v[202:205], v168 offset:34816
	ds_read_b128 v[206:209], v168 offset:35840
	ds_read_b128 v[216:219], v168 offset:36864
	ds_read_b128 v[220:223], v168 offset:37888
	ds_read_b128 v[224:227], v168 offset:38912
	ds_read_b128 v[228:231], v168 offset:39936
	global_load_lds_dwordx4 v[244:245], off
	v_lshl_add_u64 v[244:245], s[54:55], 0, v[158:159]
	s_mov_b32 m0, s59
	s_nop 0
	global_load_lds_dwordx4 v[244:245], off
	s_waitcnt vmcnt(8)
	s_waitcnt lgkmcnt(0)
	s_barrier
	s_setprio 1
	s_waitcnt lgkmcnt(0)
	v_mfma_f32_16x16x32_bf16 v[126:129], v[130:133], v[178:181], v[126:129]
	v_mfma_f32_16x16x32_bf16 v[122:125], v[138:141], v[178:181], v[122:125]
	v_mfma_f32_16x16x32_bf16 v[110:113], v[130:133], v[202:205], v[110:113]
	v_mfma_f32_16x16x32_bf16 v[106:109], v[138:141], v[202:205], v[106:109]
	v_mfma_f32_16x16x32_bf16 v[94:97], v[130:133], v[216:219], v[94:97]
	v_mfma_f32_16x16x32_bf16 v[90:93], v[138:141], v[216:219], v[90:93]
	v_mfma_f32_16x16x32_bf16 v[76:79], v[130:133], v[224:227], v[76:79]
	v_mfma_f32_16x16x32_bf16 v[72:75], v[138:141], v[224:227], v[72:75]
	v_mfma_f32_16x16x32_bf16 v[126:129], v[134:137], v[198:201], v[126:129]
	v_mfma_f32_16x16x32_bf16 v[122:125], v[142:145], v[198:201], v[122:125]
	v_mfma_f32_16x16x32_bf16 v[110:113], v[134:137], v[206:209], v[110:113]
	v_mfma_f32_16x16x32_bf16 v[106:109], v[142:145], v[206:209], v[106:109]
	v_mfma_f32_16x16x32_bf16 v[94:97], v[134:137], v[220:223], v[94:97]
	v_mfma_f32_16x16x32_bf16 v[90:93], v[142:145], v[220:223], v[90:93]
	v_mfma_f32_16x16x32_bf16 v[76:79], v[134:137], v[228:231], v[76:79]
	v_mfma_f32_16x16x32_bf16 v[72:75], v[142:145], v[228:231], v[72:75]
	v_mfma_f32_16x16x32_bf16 v[118:121], v[146:149], v[178:181], v[118:121]
	v_mfma_f32_16x16x32_bf16 v[114:117], v[170:173], v[178:181], v[114:117]
	v_mfma_f32_16x16x32_bf16 v[102:105], v[146:149], v[202:205], v[102:105]
	v_mfma_f32_16x16x32_bf16 v[98:101], v[170:173], v[202:205], v[98:101]
	v_mfma_f32_16x16x32_bf16 v[86:89], v[146:149], v[216:219], v[86:89]
	v_mfma_f32_16x16x32_bf16 v[82:85], v[170:173], v[216:219], v[82:85]
	v_mfma_f32_16x16x32_bf16 v[68:71], v[146:149], v[224:227], v[68:71]
	v_mfma_f32_16x16x32_bf16 v[64:67], v[170:173], v[224:227], v[64:67]
	v_mfma_f32_16x16x32_bf16 v[118:121], v[150:153], v[198:201], v[118:121]
	v_mfma_f32_16x16x32_bf16 v[114:117], v[174:177], v[198:201], v[114:117]
	v_mfma_f32_16x16x32_bf16 v[102:105], v[150:153], v[206:209], v[102:105]
	v_mfma_f32_16x16x32_bf16 v[98:101], v[174:177], v[206:209], v[98:101]
	v_mfma_f32_16x16x32_bf16 v[86:89], v[150:153], v[220:223], v[86:89]
	v_mfma_f32_16x16x32_bf16 v[82:85], v[174:177], v[220:223], v[82:85]
	v_mfma_f32_16x16x32_bf16 v[68:71], v[150:153], v[228:231], v[68:71]
	v_mfma_f32_16x16x32_bf16 v[64:67], v[174:177], v[228:231], v[64:67]
	s_setprio 0
	s_barrier
; #define PG8_STAGE(bufoff, gbase, voff) do { _Pragma("unroll") for (int _i = 0; _i < 2; ++_i) \
;         __builtin_amdgcn_global_load_lds((const unsigned*)((const char*)(gbase) + (voff)[_i]), (LAS unsigned*)(lds + (bufoff) + ldsw + _i * 8192), 16, 0, 0); } while (0)
; #define PG8_LDA(dst, b, h) do { _Pragma("unroll") for (int m = 0; m < 4; ++m) _Pragma("unroll") for (int k = 0; k < 2; ++k) dst[m][k] = *(const LAS bf16x8*)(lds + PG8_SA(b, h) + aoff + m * 2048 + k * 1024); } while (0)
; #define PG8_MMA(ai, bj, At, Bt) do { __builtin_amdgcn_s_setprio(1); _Pragma("unroll") for (int m = 0; m < 4; ++m) _Pragma("unroll") for (int n = 0; n < 2; ++n) _Pragma("unroll") for (int k = 0; k < 2; ++k) \
;         acc[ai][bj][m][n] = MFMA16(Bt[n][k], At[m][k], acc[ai][bj][m][n]); __builtin_amdgcn_s_setprio(0); } while (0)
; #define PG8_WAIT_V(n) asm volatile("s_waitcnt vmcnt(" #n ")" ::: "memory")
; #define PG8_WAIT_L(n) asm volatile("s_waitcnt lgkmcnt(" #n ")" ::: "memory")
; #define PG8_BAR __builtin_amdgcn_s_barrier()
; #define PG8_SCHED __builtin_amdgcn_sched_barrier(0)
; template <class Epi>
; __device__ __forceinline__ void gemm_phase(LAS unsigned char* lds, const Gemm g, const StaticOrder& S, const Epi& E, int tid_) {
;     ...
;         for (int t = 0; t < nt; t += 2) {
;     ...
;             PG8_LDA(At, 1, 1); PG8_STAGE(PG8_SB(1, 0), b3, voffB); PG8_STAGE(PG8_SB(1, 1), b3 + hsB, voffB); PG8_STAGE(PG8_SA(1, 0), a3, voffA);
;             PG8_WAIT_V(8); PG8_WAIT_L(0); PG8_BAR; PG8_MMA(1, 0, At, B0); PG8_MMA(1, 1, At, B1); PG8_BAR; PG8_SCHED;
;         }
	s_add_i32 s54, s70, s31
	v_lshl_add_u64 v[232:233], v[232:233], 0, s[6:7]
	s_mov_b32 m0, s54
	ds_read_b128 v[178:181], v168 offset:49152
	ds_read_b128 v[198:201], v168 offset:50176
	ds_read_b128 v[202:205], v168 offset:51200
	ds_read_b128 v[206:209], v168 offset:52224
	ds_read_b128 v[216:219], v168 offset:53248
	ds_read_b128 v[220:223], v168 offset:54272
	ds_read_b128 v[224:227], v168 offset:55296
	ds_read_b128 v[228:231], v168 offset:56320
	global_load_lds_dwordx4 v[232:233], off
	v_lshl_add_u64 v[232:233], v[234:235], 0, s[6:7]
	s_add_i32 m0, s54, 0x2000
	s_add_i32 s54, s71, s31
	global_load_lds_dwordx4 v[232:233], off
	v_lshl_add_u64 v[232:233], v[236:237], 0, s[6:7]
	s_mov_b32 m0, s54
	s_nop 0
	global_load_lds_dwordx4 v[232:233], off
	v_lshl_add_u64 v[232:233], v[238:239], 0, s[6:7]
	s_add_i32 m0, s54, 0x2000
	s_nop 0
	global_load_lds_dwordx4 v[232:233], off
	v_lshl_add_u64 v[232:233], v[240:241], 0, s[6:7]
	s_mov_b32 m0, s60
	s_nop 0
	global_load_lds_dwordx4 v[232:233], off
	v_lshl_add_u64 v[232:233], v[242:243], 0, s[6:7]
	s_mov_b32 m0, s61
	s_nop 0
	global_load_lds_dwordx4 v[232:233], off
	s_waitcnt vmcnt(8)
	s_waitcnt lgkmcnt(0)
	s_barrier
	s_setprio 1
	s_waitcnt lgkmcnt(0)
	v_mfma_f32_16x16x32_bf16 v[60:63], v[130:133], v[178:181], v[60:63]
	v_mfma_f32_16x16x32_bf16 v[56:59], v[138:141], v[178:181], v[56:59]
	v_mfma_f32_16x16x32_bf16 v[44:47], v[130:133], v[202:205], v[44:47]
	v_mfma_f32_16x16x32_bf16 v[40:43], v[138:141], v[202:205], v[40:43]
	v_mfma_f32_16x16x32_bf16 v[28:31], v[130:133], v[216:219], v[28:31]
	v_mfma_f32_16x16x32_bf16 v[24:27], v[138:141], v[216:219], v[24:27]
	v_mfma_f32_16x16x32_bf16 v[12:15], v[130:133], v[224:227], v[12:15]
	v_mfma_f32_16x16x32_bf16 v[8:11], v[138:141], v[224:227], v[8:11]
	v_mfma_f32_16x16x32_bf16 v[60:63], v[134:137], v[198:201], v[60:63]
	v_mfma_f32_16x16x32_bf16 v[56:59], v[142:145], v[198:201], v[56:59]
	v_mfma_f32_16x16x32_bf16 v[44:47], v[134:137], v[206:209], v[44:47]
	v_mfma_f32_16x16x32_bf16 v[40:43], v[142:145], v[206:209], v[40:43]
	v_mfma_f32_16x16x32_bf16 v[28:31], v[134:137], v[220:223], v[28:31]
	v_mfma_f32_16x16x32_bf16 v[24:27], v[142:145], v[220:223], v[24:27]
	v_mfma_f32_16x16x32_bf16 v[12:15], v[134:137], v[228:231], v[12:15]
	v_mfma_f32_16x16x32_bf16 v[8:11], v[142:145], v[228:231], v[8:11]
	v_mfma_f32_16x16x32_bf16 v[52:55], v[146:149], v[178:181], v[52:55]
	v_mfma_f32_16x16x32_bf16 v[48:51], v[170:173], v[178:181], v[48:51]
	v_mfma_f32_16x16x32_bf16 v[36:39], v[146:149], v[202:205], v[36:39]
	v_mfma_f32_16x16x32_bf16 v[32:35], v[170:173], v[202:205], v[32:35]
	v_mfma_f32_16x16x32_bf16 v[20:23], v[146:149], v[216:219], v[20:23]
	v_mfma_f32_16x16x32_bf16 v[16:19], v[170:173], v[216:219], v[16:19]
	v_mfma_f32_16x16x32_bf16 v[4:7], v[146:149], v[224:227], v[4:7]
	v_mfma_f32_16x16x32_bf16 v[0:3], v[170:173], v[224:227], v[0:3]
	v_mfma_f32_16x16x32_bf16 v[52:55], v[150:153], v[198:201], v[52:55]
	v_mfma_f32_16x16x32_bf16 v[48:51], v[174:177], v[198:201], v[48:51]
	v_mfma_f32_16x16x32_bf16 v[36:39], v[150:153], v[206:209], v[36:39]
	v_mfma_f32_16x16x32_bf16 v[32:35], v[174:177], v[206:209], v[32:35]
	v_mfma_f32_16x16x32_bf16 v[20:23], v[150:153], v[220:223], v[20:23]
	v_mfma_f32_16x16x32_bf16 v[16:19], v[174:177], v[220:223], v[16:19]
	v_mfma_f32_16x16x32_bf16 v[4:7], v[150:153], v[228:231], v[4:7]
	v_mfma_f32_16x16x32_bf16 v[0:3], v[174:177], v[228:231], v[0:3]
	s_setprio 0
	s_barrier
	s_add_u32 s28, s28, 0x100
	s_addc_u32 s29, s29, 0
	s_add_u32 s22, s22, 0x100
	s_addc_u32 s23, s23, 0
	s_cmp_ge_i32 s69, s1
	s_mov_b32 s54, s69
	s_cbranch_scc0 .LBB0_683
	s_and_b64 vcc, exec, s[50:51]
	s_cbranch_vccz .LBB0_686
